# speedup vs baseline: 1.0115x; 1.0016x over previous
; #define LAS __attribute__((address_space(3)))
; __device__ __forceinline__ unsigned cvtpk(float lo, float hi) { f32x2_t v = {lo, hi}; bf16x2_t b = __builtin_convertvector(v, bf16x2_t); return __builtin_bit_cast(unsigned, b); }
; __device__ __forceinline__ void attn_phase(LAS unsigned char* lds, const bf16_t* Z, const bf16_t* VT, bf16_t* Y, const float* subln, float lam, float lam_init, float M0, unsigned* ctr, LAS int* s_unit, int wid_s_) {
;     ...
;         __syncthreads();
;         if (jm == 0) {
;             float sw[4];
; #pragma unroll
;             for (int cb = 0; cb < 4; ++cb) sw[cb] = subln[32 * cb + rr] * (1.0f - lam_init);
; #pragma unroll
;             for (int r = 0; r < 16; ++r) { const int qrow = (r & 3) + 8 * (r >> 2) + 4 * hh; const float a = __shfl(inv, qrow);
;                 float o[4]; float ss = 0.f;
; #pragma unroll
;                 for (int cb = 0; cb < 4; ++cb) { o[cb] = O[cb][r] * a - xch[(cb * 16 + r) * 64]; ss += o[cb] * o[cb]; }
;                 ss += __shfl_xor(ss, 1); ss += __shfl_xor(ss, 2); ss += __shfl_xor(ss, 4); ss += __shfl_xor(ss, 8); ss += __shfl_xor(ss, 16);
;                 const float rn = 1.0f / sqrtf(ss * (1.f / 128.f) + NORM_EPS);
;                 LAS bf16_t* st = (LAS bf16_t*)(lds + rg * 8192) + qrow * 128 + rr;
; #pragma unroll
;                 for (int cb = 0; cb < 4; ++cb) st[32 * cb] = (bf16_t)(cvtpk(o[cb] * rn * sw[cb], 0.f) & 0xffffu);
;             }
.LBB0_1317:
	s_andn2_b64 vcc, exec, s[10:11]
	s_waitcnt lgkmcnt(0)
	s_barrier
	s_cbranch_vccnz .LBB0_1290
	global_load_dword v65, v[160:161], off
	global_load_dword v66, v[160:161], off offset:128
	global_load_dword v67, v[160:161], off offset:256
	global_load_dword v68, v[160:161], off offset:384
	v_or_b32_e32 v74, v191, v216
	v_lshlrev_b32_e32 v74, 2, v74
	ds_bpermute_b32 v82, v74, v64
	ds_read2st64_b32 v[74:75], v204 offset1:1
	ds_read2st64_b32 v[76:77], v204 offset0:16 offset1:17
	ds_read2st64_b32 v[78:79], v204 offset0:32 offset1:33
	ds_read2st64_b32 v[80:81], v204 offset0:48 offset1:49
	v_xor_b32_e32 v69, 1, v190
	s_waitcnt lgkmcnt(3)
	v_fma_f32 v32, v32, v82, -v74
	s_waitcnt lgkmcnt(2)
	v_fma_f32 v48, v48, v82, -v76
	v_mul_f32_e32 v74, v48, v48
	v_cmp_lt_i32_e32 vcc, v69, v192
	v_fmac_f32_e32 v74, v32, v32
	s_waitcnt lgkmcnt(1)
	v_fma_f32 v16, v16, v82, -v78
	v_cndmask_b32_e32 v69, v190, v69, vcc
	v_fmac_f32_e32 v74, v16, v16
	s_waitcnt lgkmcnt(0)
	v_fma_f32 v0, v0, v82, -v80
	v_lshlrev_b32_e32 v73, 2, v69
	v_fmac_f32_e32 v74, v0, v0
	s_nop 1
	v_mov_b32_dpp v76, v74 quad_perm:[1,0,3,2] row_mask:0xf bank_mask:0xf
	v_xor_b32_e32 v69, 2, v190
	v_cmp_lt_i32_e32 vcc, v69, v192
	s_lshl_b32 s26, s41, 1
	v_mov_b32_e32 v171, v97
	v_cndmask_b32_e32 v69, v190, v69, vcc
	v_lshlrev_b32_e32 v72, 2, v69
	s_waitcnt lgkmcnt(0)
	v_add_f32_e32 v74, v74, v76
	s_nop 1
	v_mov_b32_dpp v76, v74 quad_perm:[2,3,0,1] row_mask:0xf bank_mask:0xf
	v_xor_b32_e32 v69, 4, v190
	v_cmp_lt_i32_e32 vcc, v69, v192
	s_movk_i32 s15, 0x2000
	s_waitcnt lgkmcnt(0)
	v_add_f32_e32 v74, v74, v76
	v_cndmask_b32_e32 v69, v190, v69, vcc
	v_lshlrev_b32_e32 v71, 2, v69
	s_nop 1
	v_mov_b32_dpp v76, v74 row_half_mirror row_mask:0xf bank_mask:0xf
	v_xor_b32_e32 v69, 8, v190
	v_cmp_lt_i32_e32 vcc, v69, v192
	s_waitcnt lgkmcnt(0)
	v_add_f32_e32 v74, v74, v76
	v_cndmask_b32_e32 v69, v190, v69, vcc
	v_lshlrev_b32_e32 v70, 2, v69
	s_nop 1
	v_mov_b32_dpp v76, v74 row_mirror row_mask:0xf bank_mask:0xf
	v_xor_b32_e32 v69, 16, v190
	v_cmp_lt_i32_e32 vcc, v69, v192
	s_waitcnt lgkmcnt(0)
	v_add_f32_e32 v74, v74, v76
	v_cndmask_b32_e32 v69, v190, v69, vcc
	v_lshlrev_b32_e32 v69, 2, v69
	ds_bpermute_b32 v76, v69, v74
	s_waitcnt lgkmcnt(0)
	v_add_f32_e32 v74, v74, v76
	v_fmamk_f32 v74, v74, 0x3c000000, v185
	v_cmp_gt_f32_e32 vcc, s36, v74
	v_mul_f32_e32 v76, 0x4f800000, v74
	s_waitcnt vmcnt(3)
	v_mul_f32_e32 v65, v202, v65
	v_cndmask_b32_e32 v74, v74, v76, vcc
	v_sqrt_f32_e32 v76, v74
	s_waitcnt vmcnt(0)
	v_mul_f32_e32 v68, v202, v68
	v_mul_f32_e32 v66, v202, v66
	v_mul_f32_e32 v67, v202, v67
	v_add_u32_e32 v78, -1, v76
	v_fma_f32 v80, -v78, v76, v74
	v_cmp_ge_f32_e64 s[2:3], 0, v80
	v_add_u32_e32 v80, 1, v76
	s_nop 0
	v_cndmask_b32_e64 v78, v76, v78, s[2:3]
	v_fma_f32 v76, -v80, v76, v74
	v_cmp_lt_f32_e64 s[2:3], 0, v76
	s_nop 1
	v_cndmask_b32_e64 v76, v78, v80, s[2:3]
	v_mul_f32_e32 v78, 0x37800000, v76
	v_cndmask_b32_e32 v76, v76, v78, vcc
	v_cmp_class_f32_e32 vcc, v74, v186
	s_nop 1
	v_cndmask_b32_e32 v74, v76, v74, vcc
	v_div_scale_f32 v76, s[2:3], v74, v74, 1.0
	v_rcp_f32_e32 v78, v76
	s_nop 0
	v_fma_f32 v80, -v76, v78, 1.0
	v_fmac_f32_e32 v78, v80, v78
	v_div_scale_f32 v80, vcc, 1.0, v74, 1.0
	v_mul_f32_e32 v82, v80, v78
	v_fma_f32 v83, -v76, v82, v80
	v_fmac_f32_e32 v82, v83, v78
	v_fma_f32 v76, -v76, v82, v80
	v_div_fmas_f32 v76, v76, v78, v82
	v_div_fixup_f32 v74, v76, v74, 1.0
	v_mul_f32_e32 v0, v0, v74
	v_mul_f32_e32 v0, v68, v0
	v_cvt_pk_bf16_f32 v0, v0, s0
	ds_write_b16 v241, v0 offset:192
	v_or_b32_e32 v0, 1, v216
	v_or_b32_e32 v0, v191, v0
	v_mul_f32_e32 v32, v32, v74
	v_lshlrev_b32_e32 v0, 2, v0
	v_mul_f32_e32 v32, v65, v32
	ds_bpermute_b32 v0, v0, v64
	v_cvt_pk_bf16_f32 v32, v32, s0
	ds_write_b16 v241, v32
	v_mul_f32_e32 v32, v48, v74
	v_mul_f32_e32 v32, v66, v32
	v_mul_f32_e32 v16, v16, v74
	v_cvt_pk_bf16_f32 v32, v32, s0
	v_mul_f32_e32 v16, v67, v16
	ds_write_b16 v241, v32 offset:64
	v_cvt_pk_bf16_f32 v16, v16, s0
	s_waitcnt lgkmcnt(2)
	v_fma_f32 v32, v49, v0, -v77
	ds_write_b16 v241, v16 offset:128
	v_fma_f32 v16, v33, v0, -v75
	v_mul_f32_e32 v33, v32, v32
	v_fmac_f32_e32 v33, v16, v16
	v_fma_f32 v17, v17, v0, -v79
	v_fmac_f32_e32 v33, v17, v17
	v_fma_f32 v0, v1, v0, -v81
	v_fmac_f32_e32 v33, v0, v0
	s_nop 1
	v_mov_b32_dpp v1, v33 quad_perm:[1,0,3,2] row_mask:0xf bank_mask:0xf
	s_waitcnt lgkmcnt(0)
	v_add_f32_e32 v1, v33, v1
	s_nop 1
	v_mov_b32_dpp v33, v1 quad_perm:[2,3,0,1] row_mask:0xf bank_mask:0xf
	s_waitcnt lgkmcnt(0)
	v_add_f32_e32 v1, v1, v33
	s_nop 1
	v_mov_b32_dpp v33, v1 row_half_mirror row_mask:0xf bank_mask:0xf
	s_waitcnt lgkmcnt(0)
	v_add_f32_e32 v1, v1, v33
	s_nop 1
	v_mov_b32_dpp v33, v1 row_mirror row_mask:0xf bank_mask:0xf
	s_waitcnt lgkmcnt(0)
	v_add_f32_e32 v1, v1, v33
	ds_bpermute_b32 v33, v69, v1
	s_waitcnt lgkmcnt(0)
; #define LAS __attribute__((address_space(3)))
; __device__ __forceinline__ unsigned cvtpk(float lo, float hi) { f32x2_t v = {lo, hi}; bf16x2_t b = __builtin_convertvector(v, bf16x2_t); return __builtin_bit_cast(unsigned, b); }
; __device__ __forceinline__ void attn_phase(LAS unsigned char* lds, const bf16_t* Z, const bf16_t* VT, bf16_t* Y, const float* subln, float lam, float lam_init, float M0, unsigned* ctr, LAS int* s_unit, int wid_s_) {
;     ...
;             for (int r = 0; r < 16; ++r) { const int qrow = (r & 3) + 8 * (r >> 2) + 4 * hh; const float a = __shfl(inv, qrow);
;                 float o[4]; float ss = 0.f;
; #pragma unroll
;                 for (int cb = 0; cb < 4; ++cb) { o[cb] = O[cb][r] * a - xch[(cb * 16 + r) * 64]; ss += o[cb] * o[cb]; }
;                 ss += __shfl_xor(ss, 1); ss += __shfl_xor(ss, 2); ss += __shfl_xor(ss, 4); ss += __shfl_xor(ss, 8); ss += __shfl_xor(ss, 16);
;                 const float rn = 1.0f / sqrtf(ss * (1.f / 128.f) + NORM_EPS);
;                 LAS bf16_t* st = (LAS bf16_t*)(lds + rg * 8192) + qrow * 128 + rr;
; #pragma unroll
;                 for (int cb = 0; cb < 4; ++cb) st[32 * cb] = (bf16_t)(cvtpk(o[cb] * rn * sw[cb], 0.f) & 0xffffu);
;             }
	v_add_f32_e32 v1, v1, v33
	v_fmamk_f32 v1, v1, 0x3c000000, v185
	v_cmp_gt_f32_e32 vcc, s36, v1
	v_mul_f32_e32 v33, 0x4f800000, v1
	s_nop 0
	v_cndmask_b32_e32 v1, v1, v33, vcc
	v_sqrt_f32_e32 v33, v1
	s_nop 0
	v_add_u32_e32 v48, -1, v33
	v_fma_f32 v49, -v48, v33, v1
	v_cmp_ge_f32_e64 s[2:3], 0, v49
	v_add_u32_e32 v49, 1, v33
	s_nop 0
	v_cndmask_b32_e64 v48, v33, v48, s[2:3]
	v_fma_f32 v33, -v49, v33, v1
	v_cmp_lt_f32_e64 s[2:3], 0, v33
	s_nop 1
	v_cndmask_b32_e64 v33, v48, v49, s[2:3]
	v_mul_f32_e32 v48, 0x37800000, v33
	v_cndmask_b32_e32 v33, v33, v48, vcc
	v_cmp_class_f32_e32 vcc, v1, v186
	s_nop 1
	v_cndmask_b32_e32 v1, v33, v1, vcc
	v_div_scale_f32 v33, s[2:3], v1, v1, 1.0
	v_rcp_f32_e32 v48, v33
	s_nop 0
	v_fma_f32 v49, -v33, v48, 1.0
	v_fmac_f32_e32 v48, v49, v48
	v_div_scale_f32 v49, vcc, 1.0, v1, 1.0
	v_mul_f32_e32 v74, v49, v48
	v_fma_f32 v75, -v33, v74, v49
	v_fmac_f32_e32 v74, v75, v48
	v_fma_f32 v33, -v33, v74, v49
	v_div_fmas_f32 v33, v33, v48, v74
	v_div_fixup_f32 v1, v33, v1, 1.0
	v_mul_f32_e32 v16, v16, v1
	v_mul_f32_e32 v16, v65, v16
	v_cvt_pk_bf16_f32 v16, v16, s0
	ds_write_b16 v242, v16
	v_mul_f32_e32 v16, v32, v1
	v_mul_f32_e32 v0, v0, v1
	v_mul_f32_e32 v16, v66, v16
	v_mul_f32_e32 v0, v68, v0
	v_cvt_pk_bf16_f32 v16, v16, s0
	v_cvt_pk_bf16_f32 v0, v0, s0
	ds_write_b16 v242, v16 offset:64
	v_mul_f32_e32 v16, v17, v1
	ds_write_b16 v242, v0 offset:192
	v_or_b32_e32 v0, 2, v216
	v_mul_f32_e32 v16, v67, v16
	v_or_b32_e32 v0, v191, v0
	v_cvt_pk_bf16_f32 v16, v16, s0
	v_lshlrev_b32_e32 v0, 2, v0
	ds_write_b16 v242, v16 offset:128
	ds_bpermute_b32 v0, v0, v64
	ds_read2st64_b32 v[16:17], v204 offset0:2 offset1:3
	ds_read2st64_b32 v[32:33], v204 offset0:18 offset1:19
	ds_read2st64_b32 v[48:49], v204 offset0:34 offset1:35
	ds_read2st64_b32 v[74:75], v204 offset0:50 offset1:51
	s_waitcnt lgkmcnt(3)
	v_fma_f32 v1, v34, v0, -v16
	s_waitcnt lgkmcnt(2)
	v_fma_f32 v16, v50, v0, -v32
	v_mul_f32_e32 v32, v16, v16
	v_fmac_f32_e32 v32, v1, v1
	s_waitcnt lgkmcnt(1)
	v_fma_f32 v18, v18, v0, -v48
	v_fmac_f32_e32 v32, v18, v18
	s_waitcnt lgkmcnt(0)
	v_fma_f32 v0, v2, v0, -v74
	v_fmac_f32_e32 v32, v0, v0
	s_nop 1
	v_mov_b32_dpp v2, v32 quad_perm:[1,0,3,2] row_mask:0xf bank_mask:0xf
	s_waitcnt lgkmcnt(0)
	v_add_f32_e32 v2, v32, v2
	s_nop 1
	v_mov_b32_dpp v32, v2 quad_perm:[2,3,0,1] row_mask:0xf bank_mask:0xf
	s_waitcnt lgkmcnt(0)
	v_add_f32_e32 v2, v2, v32
	s_nop 1
	v_mov_b32_dpp v32, v2 row_half_mirror row_mask:0xf bank_mask:0xf
	s_waitcnt lgkmcnt(0)
	v_add_f32_e32 v2, v2, v32
	s_nop 1
	v_mov_b32_dpp v32, v2 row_mirror row_mask:0xf bank_mask:0xf
	s_waitcnt lgkmcnt(0)
	v_add_f32_e32 v2, v2, v32
	ds_bpermute_b32 v32, v69, v2
	s_waitcnt lgkmcnt(0)
	v_add_f32_e32 v2, v2, v32
	v_fmamk_f32 v2, v2, 0x3c000000, v185
	v_cmp_gt_f32_e32 vcc, s36, v2
	v_mul_f32_e32 v32, 0x4f800000, v2
	s_nop 0
	v_cndmask_b32_e32 v2, v2, v32, vcc
	v_sqrt_f32_e32 v32, v2
	s_nop 0
	v_add_u32_e32 v34, -1, v32
	v_fma_f32 v48, -v34, v32, v2
	v_cmp_ge_f32_e64 s[2:3], 0, v48
	v_add_u32_e32 v48, 1, v32
	s_nop 0
	v_cndmask_b32_e64 v34, v32, v34, s[2:3]
	v_fma_f32 v32, -v48, v32, v2
	v_cmp_lt_f32_e64 s[2:3], 0, v32
	s_nop 1
	v_cndmask_b32_e64 v32, v34, v48, s[2:3]
	v_mul_f32_e32 v34, 0x37800000, v32
	v_cndmask_b32_e32 v32, v32, v34, vcc
	v_cmp_class_f32_e32 vcc, v2, v186
	s_nop 1
	v_cndmask_b32_e32 v2, v32, v2, vcc
	v_div_scale_f32 v32, s[2:3], v2, v2, 1.0
	v_rcp_f32_e32 v34, v32
	s_nop 0
	v_fma_f32 v48, -v32, v34, 1.0
	v_fmac_f32_e32 v34, v48, v34
	v_div_scale_f32 v48, vcc, 1.0, v2, 1.0
	v_mul_f32_e32 v50, v48, v34
	v_fma_f32 v74, -v32, v50, v48
	v_fmac_f32_e32 v50, v74, v34
	v_fma_f32 v32, -v32, v50, v48
	v_div_fmas_f32 v32, v32, v34, v50
	v_div_fixup_f32 v2, v32, v2, 1.0
	v_mul_f32_e32 v0, v0, v2
	v_mul_f32_e32 v0, v68, v0
	v_cvt_pk_bf16_f32 v0, v0, s0
	v_mul_f32_e32 v1, v1, v2
	ds_write_b16 v243, v0 offset:192
	v_or_b32_e32 v0, 3, v216
	v_mul_f32_e32 v1, v65, v1
	v_or_b32_e32 v0, v191, v0
	v_cvt_pk_bf16_f32 v1, v1, s0
	v_lshlrev_b32_e32 v0, 2, v0
	ds_write_b16 v243, v1
	v_mul_f32_e32 v1, v16, v2
	ds_bpermute_b32 v0, v0, v64
	v_mul_f32_e32 v1, v66, v1
	v_cvt_pk_bf16_f32 v1, v1, s0
	ds_write_b16 v243, v1 offset:64
	v_mul_f32_e32 v1, v18, v2
	v_mul_f32_e32 v1, v67, v1
	v_cvt_pk_bf16_f32 v1, v1, s0
	s_waitcnt lgkmcnt(1)
	v_fma_f32 v2, v51, v0, -v33
	ds_write_b16 v243, v1 offset:128
	v_fma_f32 v1, v35, v0, -v17
	v_mul_f32_e32 v16, v2, v2
	v_fmac_f32_e32 v16, v1, v1
	v_fma_f32 v17, v19, v0, -v49
	v_fmac_f32_e32 v16, v17, v17
	v_fma_f32 v0, v3, v0, -v75
	v_fmac_f32_e32 v16, v0, v0
	s_nop 1
	v_mov_b32_dpp v3, v16 quad_perm:[1,0,3,2] row_mask:0xf bank_mask:0xf
	s_waitcnt lgkmcnt(0)
	v_add_f32_e32 v3, v16, v3
	s_nop 1
	v_mov_b32_dpp v16, v3 quad_perm:[2,3,0,1] row_mask:0xf bank_mask:0xf
	s_waitcnt lgkmcnt(0)
	v_add_f32_e32 v3, v3, v16
	s_nop 1
	v_mov_b32_dpp v16, v3 row_half_mirror row_mask:0xf bank_mask:0xf
	s_waitcnt lgkmcnt(0)
	v_add_f32_e32 v3, v3, v16
	s_nop 1
	v_mov_b32_dpp v16, v3 row_mirror row_mask:0xf bank_mask:0xf
	s_waitcnt lgkmcnt(0)
	v_add_f32_e32 v3, v3, v16
	ds_bpermute_b32 v16, v69, v3
	s_waitcnt lgkmcnt(0)
; #define LAS __attribute__((address_space(3)))
; __device__ __forceinline__ unsigned cvtpk(float lo, float hi) { f32x2_t v = {lo, hi}; bf16x2_t b = __builtin_convertvector(v, bf16x2_t); return __builtin_bit_cast(unsigned, b); }
; __device__ __forceinline__ void attn_phase(LAS unsigned char* lds, const bf16_t* Z, const bf16_t* VT, bf16_t* Y, const float* subln, float lam, float lam_init, float M0, unsigned* ctr, LAS int* s_unit, int wid_s_) {
;     ...
;             for (int r = 0; r < 16; ++r) { const int qrow = (r & 3) + 8 * (r >> 2) + 4 * hh; const float a = __shfl(inv, qrow);
;                 float o[4]; float ss = 0.f;
; #pragma unroll
;                 for (int cb = 0; cb < 4; ++cb) { o[cb] = O[cb][r] * a - xch[(cb * 16 + r) * 64]; ss += o[cb] * o[cb]; }
;                 ss += __shfl_xor(ss, 1); ss += __shfl_xor(ss, 2); ss += __shfl_xor(ss, 4); ss += __shfl_xor(ss, 8); ss += __shfl_xor(ss, 16);
;                 const float rn = 1.0f / sqrtf(ss * (1.f / 128.f) + NORM_EPS);
;                 LAS bf16_t* st = (LAS bf16_t*)(lds + rg * 8192) + qrow * 128 + rr;
; #pragma unroll
;                 for (int cb = 0; cb < 4; ++cb) st[32 * cb] = (bf16_t)(cvtpk(o[cb] * rn * sw[cb], 0.f) & 0xffffu);
;             }
	v_add_f32_e32 v3, v3, v16
	v_fmamk_f32 v3, v3, 0x3c000000, v185
	v_cmp_gt_f32_e32 vcc, s36, v3
	v_mul_f32_e32 v16, 0x4f800000, v3
	s_nop 0
	v_cndmask_b32_e32 v3, v3, v16, vcc
	v_sqrt_f32_e32 v16, v3
	s_nop 0
	v_add_u32_e32 v18, -1, v16
	v_fma_f32 v19, -v18, v16, v3
	v_cmp_ge_f32_e64 s[2:3], 0, v19
	v_add_u32_e32 v19, 1, v16
	s_nop 0
	v_cndmask_b32_e64 v18, v16, v18, s[2:3]
	v_fma_f32 v16, -v19, v16, v3
	v_cmp_lt_f32_e64 s[2:3], 0, v16
	s_nop 1
	v_cndmask_b32_e64 v16, v18, v19, s[2:3]
	v_mul_f32_e32 v18, 0x37800000, v16
	v_cndmask_b32_e32 v16, v16, v18, vcc
	v_cmp_class_f32_e32 vcc, v3, v186
	s_nop 1
	v_cndmask_b32_e32 v3, v16, v3, vcc
	v_div_scale_f32 v16, s[2:3], v3, v3, 1.0
	v_rcp_f32_e32 v18, v16
	s_nop 0
	v_fma_f32 v19, -v16, v18, 1.0
	v_fmac_f32_e32 v18, v19, v18
	v_div_scale_f32 v19, vcc, 1.0, v3, 1.0
	v_mul_f32_e32 v32, v19, v18
	v_fma_f32 v33, -v16, v32, v19
	v_fmac_f32_e32 v32, v33, v18
	v_fma_f32 v16, -v16, v32, v19
	v_div_fmas_f32 v16, v16, v18, v32
	v_div_fixup_f32 v3, v16, v3, 1.0
	v_mul_f32_e32 v1, v1, v3
	v_mul_f32_e32 v0, v0, v3
	v_mul_f32_e32 v1, v65, v1
	v_mul_f32_e32 v0, v68, v0
	v_cvt_pk_bf16_f32 v1, v1, s0
	v_cvt_pk_bf16_f32 v0, v0, s0
	ds_write_b16 v244, v1
	v_mul_f32_e32 v1, v2, v3
	ds_write_b16 v244, v0 offset:192
	v_or_b32_e32 v0, 8, v216
	v_mul_f32_e32 v1, v66, v1
	v_or_b32_e32 v0, v191, v0
	v_cvt_pk_bf16_f32 v1, v1, s0
	v_lshlrev_b32_e32 v0, 2, v0
	ds_write_b16 v244, v1 offset:64
	v_mul_f32_e32 v1, v17, v3
	ds_bpermute_b32 v0, v0, v64
	ds_read2st64_b32 v[2:3], v204 offset0:4 offset1:5
	ds_read2st64_b32 v[16:17], v204 offset0:20 offset1:21
	ds_read2st64_b32 v[18:19], v204 offset0:36 offset1:37
	ds_read2st64_b32 v[32:33], v204 offset0:52 offset1:53
	v_mul_f32_e32 v1, v67, v1
	v_cvt_pk_bf16_f32 v1, v1, s0
	ds_write_b16 v244, v1 offset:128
	s_waitcnt lgkmcnt(4)
	v_fma_f32 v1, v36, v0, -v2
	s_waitcnt lgkmcnt(3)
	v_fma_f32 v2, v52, v0, -v16
	v_mul_f32_e32 v16, v2, v2
	v_fmac_f32_e32 v16, v1, v1
	s_waitcnt lgkmcnt(2)
	v_fma_f32 v18, v20, v0, -v18
	v_fmac_f32_e32 v16, v18, v18
	s_waitcnt lgkmcnt(1)
	v_fma_f32 v0, v4, v0, -v32
	v_fmac_f32_e32 v16, v0, v0
	s_nop 1
	v_mov_b32_dpp v4, v16 quad_perm:[1,0,3,2] row_mask:0xf bank_mask:0xf
	s_waitcnt lgkmcnt(0)
	v_add_f32_e32 v4, v16, v4
	s_nop 1
	v_mov_b32_dpp v16, v4 quad_perm:[2,3,0,1] row_mask:0xf bank_mask:0xf
	s_waitcnt lgkmcnt(0)
	v_add_f32_e32 v4, v4, v16
	s_nop 1
	v_mov_b32_dpp v16, v4 row_half_mirror row_mask:0xf bank_mask:0xf
	s_waitcnt lgkmcnt(0)
	v_add_f32_e32 v4, v4, v16
	s_nop 1
	v_mov_b32_dpp v16, v4 row_mirror row_mask:0xf bank_mask:0xf
	s_waitcnt lgkmcnt(0)
	v_add_f32_e32 v4, v4, v16
	ds_bpermute_b32 v16, v69, v4
	s_waitcnt lgkmcnt(0)
	v_add_f32_e32 v4, v4, v16
	v_fmamk_f32 v4, v4, 0x3c000000, v185
	v_cmp_gt_f32_e32 vcc, s36, v4
	v_mul_f32_e32 v16, 0x4f800000, v4
	s_nop 0
	v_cndmask_b32_e32 v4, v4, v16, vcc
	v_sqrt_f32_e32 v16, v4
	s_nop 0
	v_add_u32_e32 v20, -1, v16
	v_fma_f32 v32, -v20, v16, v4
	v_cmp_ge_f32_e64 s[2:3], 0, v32
	v_add_u32_e32 v32, 1, v16
	s_nop 0
	v_cndmask_b32_e64 v20, v16, v20, s[2:3]
	v_fma_f32 v16, -v32, v16, v4
	v_cmp_lt_f32_e64 s[2:3], 0, v16
	s_nop 1
	v_cndmask_b32_e64 v16, v20, v32, s[2:3]
	v_mul_f32_e32 v20, 0x37800000, v16
	v_cndmask_b32_e32 v16, v16, v20, vcc
	v_cmp_class_f32_e32 vcc, v4, v186
	s_nop 1
	v_cndmask_b32_e32 v4, v16, v4, vcc
	v_div_scale_f32 v16, s[2:3], v4, v4, 1.0
	v_rcp_f32_e32 v20, v16
	s_nop 0
	v_fma_f32 v32, -v16, v20, 1.0
	v_fmac_f32_e32 v20, v32, v20
	v_div_scale_f32 v32, vcc, 1.0, v4, 1.0
	v_mul_f32_e32 v34, v32, v20
	v_fma_f32 v35, -v16, v34, v32
	v_fmac_f32_e32 v34, v35, v20
	v_fma_f32 v16, -v16, v34, v32
	v_div_fmas_f32 v16, v16, v20, v34
	v_div_fixup_f32 v4, v16, v4, 1.0
	v_mul_f32_e32 v0, v0, v4
	v_mul_f32_e32 v0, v68, v0
	v_cvt_pk_bf16_f32 v0, v0, s0
	v_mul_f32_e32 v1, v1, v4
	ds_write_b16 v245, v0 offset:192
	v_or_b32_e32 v0, 9, v216
	v_mul_f32_e32 v1, v65, v1
	v_or_b32_e32 v0, v191, v0
	v_cvt_pk_bf16_f32 v1, v1, s0
	v_lshlrev_b32_e32 v0, 2, v0
	ds_write_b16 v245, v1
	v_mul_f32_e32 v1, v2, v4
	ds_bpermute_b32 v0, v0, v64
	v_mul_f32_e32 v1, v66, v1
	v_cvt_pk_bf16_f32 v1, v1, s0
	ds_write_b16 v245, v1 offset:64
	v_mul_f32_e32 v1, v18, v4
	v_mul_f32_e32 v1, v67, v1
	v_cvt_pk_bf16_f32 v1, v1, s0
	s_waitcnt lgkmcnt(1)
	v_fma_f32 v2, v53, v0, -v17
	ds_write_b16 v245, v1 offset:128
	v_fma_f32 v1, v37, v0, -v3
	v_mul_f32_e32 v3, v2, v2
	v_fmac_f32_e32 v3, v1, v1
	v_fma_f32 v4, v21, v0, -v19
	v_fmac_f32_e32 v3, v4, v4
	v_fma_f32 v0, v5, v0, -v33
	v_fmac_f32_e32 v3, v0, v0
	s_nop 1
	v_mov_b32_dpp v5, v3 quad_perm:[1,0,3,2] row_mask:0xf bank_mask:0xf
	s_waitcnt lgkmcnt(0)
	v_add_f32_e32 v3, v3, v5
	s_nop 1
	v_mov_b32_dpp v5, v3 quad_perm:[2,3,0,1] row_mask:0xf bank_mask:0xf
	s_waitcnt lgkmcnt(0)
	v_add_f32_e32 v3, v3, v5
	s_nop 1
	v_mov_b32_dpp v5, v3 row_half_mirror row_mask:0xf bank_mask:0xf
	s_waitcnt lgkmcnt(0)
	v_add_f32_e32 v3, v3, v5
	s_nop 1
	v_mov_b32_dpp v5, v3 row_mirror row_mask:0xf bank_mask:0xf
	s_waitcnt lgkmcnt(0)
	v_add_f32_e32 v3, v3, v5
	ds_bpermute_b32 v5, v69, v3
	s_waitcnt lgkmcnt(0)
; #define LAS __attribute__((address_space(3)))
; __device__ __forceinline__ unsigned cvtpk(float lo, float hi) { f32x2_t v = {lo, hi}; bf16x2_t b = __builtin_convertvector(v, bf16x2_t); return __builtin_bit_cast(unsigned, b); }
; __device__ __forceinline__ void attn_phase(LAS unsigned char* lds, const bf16_t* Z, const bf16_t* VT, bf16_t* Y, const float* subln, float lam, float lam_init, float M0, unsigned* ctr, LAS int* s_unit, int wid_s_) {
;     ...
;             for (int r = 0; r < 16; ++r) { const int qrow = (r & 3) + 8 * (r >> 2) + 4 * hh; const float a = __shfl(inv, qrow);
;                 float o[4]; float ss = 0.f;
; #pragma unroll
;                 for (int cb = 0; cb < 4; ++cb) { o[cb] = O[cb][r] * a - xch[(cb * 16 + r) * 64]; ss += o[cb] * o[cb]; }
;                 ss += __shfl_xor(ss, 1); ss += __shfl_xor(ss, 2); ss += __shfl_xor(ss, 4); ss += __shfl_xor(ss, 8); ss += __shfl_xor(ss, 16);
;                 const float rn = 1.0f / sqrtf(ss * (1.f / 128.f) + NORM_EPS);
;                 LAS bf16_t* st = (LAS bf16_t*)(lds + rg * 8192) + qrow * 128 + rr;
; #pragma unroll
;                 for (int cb = 0; cb < 4; ++cb) st[32 * cb] = (bf16_t)(cvtpk(o[cb] * rn * sw[cb], 0.f) & 0xffffu);
;             }
	v_add_f32_e32 v3, v3, v5
	v_fmamk_f32 v3, v3, 0x3c000000, v185
	v_cmp_gt_f32_e32 vcc, s36, v3
	v_mul_f32_e32 v5, 0x4f800000, v3
	s_nop 0
	v_cndmask_b32_e32 v3, v3, v5, vcc
	v_sqrt_f32_e32 v5, v3
	s_nop 0
	v_add_u32_e32 v16, -1, v5
	v_fma_f32 v17, -v16, v5, v3
	v_cmp_ge_f32_e64 s[2:3], 0, v17
	v_add_u32_e32 v17, 1, v5
	s_nop 0
	v_cndmask_b32_e64 v16, v5, v16, s[2:3]
	v_fma_f32 v5, -v17, v5, v3
	v_cmp_lt_f32_e64 s[2:3], 0, v5
	s_nop 1
	v_cndmask_b32_e64 v5, v16, v17, s[2:3]
	v_mul_f32_e32 v16, 0x37800000, v5
	v_cndmask_b32_e32 v5, v5, v16, vcc
	v_cmp_class_f32_e32 vcc, v3, v186
	s_nop 1
	v_cndmask_b32_e32 v3, v5, v3, vcc
	v_div_scale_f32 v5, s[2:3], v3, v3, 1.0
	v_rcp_f32_e32 v16, v5
	s_nop 0
	v_fma_f32 v17, -v5, v16, 1.0
	v_fmac_f32_e32 v16, v17, v16
	v_div_scale_f32 v17, vcc, 1.0, v3, 1.0
	v_mul_f32_e32 v18, v17, v16
	v_fma_f32 v19, -v5, v18, v17
	v_fmac_f32_e32 v18, v19, v16
	v_fma_f32 v5, -v5, v18, v17
	v_div_fmas_f32 v5, v5, v16, v18
	v_div_fixup_f32 v3, v5, v3, 1.0
	v_mul_f32_e32 v1, v1, v3
	v_mul_f32_e32 v1, v65, v1
	v_cvt_pk_bf16_f32 v1, v1, s0
	ds_write_b16 v246, v1
	v_mul_f32_e32 v1, v2, v3
	v_mul_f32_e32 v0, v0, v3
	v_mul_f32_e32 v1, v66, v1
	v_mul_f32_e32 v0, v68, v0
	v_cvt_pk_bf16_f32 v1, v1, s0
	v_cvt_pk_bf16_f32 v0, v0, s0
	ds_write_b16 v246, v1 offset:64
	v_mul_f32_e32 v1, v4, v3
	ds_write_b16 v246, v0 offset:192
	v_or_b32_e32 v0, 10, v216
	v_mul_f32_e32 v1, v67, v1
	v_or_b32_e32 v0, v191, v0
	v_cvt_pk_bf16_f32 v1, v1, s0
	v_lshlrev_b32_e32 v0, 2, v0
	ds_write_b16 v246, v1 offset:128
	ds_bpermute_b32 v18, v0, v64
	ds_read2st64_b32 v[0:1], v204 offset0:6 offset1:7
	ds_read2st64_b32 v[2:3], v204 offset0:22 offset1:23
	ds_read2st64_b32 v[4:5], v204 offset0:38 offset1:39
	ds_read2st64_b32 v[16:17], v204 offset0:54 offset1:55
	s_waitcnt lgkmcnt(3)
	v_fma_f32 v0, v38, v18, -v0
	s_waitcnt lgkmcnt(2)
	v_fma_f32 v2, v54, v18, -v2
	v_mul_f32_e32 v19, v2, v2
	v_fmac_f32_e32 v19, v0, v0
	s_waitcnt lgkmcnt(1)
	v_fma_f32 v4, v22, v18, -v4
	v_fmac_f32_e32 v19, v4, v4
	s_waitcnt lgkmcnt(0)
	v_fma_f32 v6, v6, v18, -v16
	v_fmac_f32_e32 v19, v6, v6
	s_nop 1
	v_mov_b32_dpp v16, v19 quad_perm:[1,0,3,2] row_mask:0xf bank_mask:0xf
	s_waitcnt lgkmcnt(0)
	v_add_f32_e32 v16, v19, v16
	s_nop 1
	v_mov_b32_dpp v18, v16 quad_perm:[2,3,0,1] row_mask:0xf bank_mask:0xf
	s_waitcnt lgkmcnt(0)
	v_add_f32_e32 v16, v16, v18
	s_nop 1
	v_mov_b32_dpp v18, v16 row_half_mirror row_mask:0xf bank_mask:0xf
	s_waitcnt lgkmcnt(0)
	v_add_f32_e32 v16, v16, v18
	s_nop 1
	v_mov_b32_dpp v18, v16 row_mirror row_mask:0xf bank_mask:0xf
	s_waitcnt lgkmcnt(0)
	v_add_f32_e32 v16, v16, v18
	ds_bpermute_b32 v18, v69, v16
	s_waitcnt lgkmcnt(0)
	v_add_f32_e32 v16, v16, v18
	v_fmamk_f32 v16, v16, 0x3c000000, v185
	v_cmp_gt_f32_e32 vcc, s36, v16
	v_mul_f32_e32 v18, 0x4f800000, v16
	s_nop 0
	v_cndmask_b32_e32 v16, v16, v18, vcc
	v_sqrt_f32_e32 v18, v16
	s_nop 0
	v_add_u32_e32 v19, -1, v18
	v_fma_f32 v20, -v19, v18, v16
	v_cmp_ge_f32_e64 s[2:3], 0, v20
	v_add_u32_e32 v20, 1, v18
	s_nop 0
	v_cndmask_b32_e64 v19, v18, v19, s[2:3]
	v_fma_f32 v18, -v20, v18, v16
	v_cmp_lt_f32_e64 s[2:3], 0, v18
	s_nop 1
	v_cndmask_b32_e64 v18, v19, v20, s[2:3]
	v_mul_f32_e32 v19, 0x37800000, v18
	v_cndmask_b32_e32 v18, v18, v19, vcc
	v_cmp_class_f32_e32 vcc, v16, v186
	s_nop 1
	v_cndmask_b32_e32 v16, v18, v16, vcc
	v_div_scale_f32 v18, s[2:3], v16, v16, 1.0
	v_rcp_f32_e32 v19, v18
	s_nop 0
	v_fma_f32 v20, -v18, v19, 1.0
	v_fmac_f32_e32 v19, v20, v19
	v_div_scale_f32 v20, vcc, 1.0, v16, 1.0
	v_mul_f32_e32 v21, v20, v19
	v_fma_f32 v22, -v18, v21, v20
	v_fmac_f32_e32 v21, v22, v19
	v_fma_f32 v18, -v18, v21, v20
	v_div_fmas_f32 v18, v18, v19, v21
	v_div_fixup_f32 v16, v18, v16, 1.0
	v_mul_f32_e32 v0, v0, v16
	v_mul_f32_e32 v0, v65, v0
	v_cvt_pk_bf16_f32 v0, v0, s0
	ds_write_b16 v247, v0
	v_mul_f32_e32 v0, v2, v16
	v_mul_f32_e32 v0, v66, v0
	v_cvt_pk_bf16_f32 v0, v0, s0
	ds_write_b16 v247, v0 offset:64
	v_mul_f32_e32 v0, v4, v16
	v_mul_f32_e32 v0, v67, v0
	v_cvt_pk_bf16_f32 v0, v0, s0
	ds_write_b16 v247, v0 offset:128
	v_mul_f32_e32 v0, v6, v16
	v_mul_f32_e32 v0, v68, v0
	v_cvt_pk_bf16_f32 v0, v0, s0
	ds_write_b16 v247, v0 offset:192
	v_or_b32_e32 v0, 11, v216
	v_or_b32_e32 v0, v191, v0
	v_lshlrev_b32_e32 v0, 2, v0
	ds_bpermute_b32 v0, v0, v64
	s_waitcnt lgkmcnt(0)
	v_fma_f32 v2, v55, v0, -v3
	v_fma_f32 v1, v39, v0, -v1
	v_mul_f32_e32 v3, v2, v2
	v_fmac_f32_e32 v3, v1, v1
	v_fma_f32 v4, v23, v0, -v5
	v_fmac_f32_e32 v3, v4, v4
	v_fma_f32 v0, v7, v0, -v17
	v_fmac_f32_e32 v3, v0, v0
	s_nop 1
	v_mov_b32_dpp v5, v3 quad_perm:[1,0,3,2] row_mask:0xf bank_mask:0xf
	s_waitcnt lgkmcnt(0)
	v_add_f32_e32 v3, v3, v5
	s_nop 1
	v_mov_b32_dpp v5, v3 quad_perm:[2,3,0,1] row_mask:0xf bank_mask:0xf
	s_waitcnt lgkmcnt(0)
	v_add_f32_e32 v3, v3, v5
	s_nop 1
	v_mov_b32_dpp v5, v3 row_half_mirror row_mask:0xf bank_mask:0xf
	s_waitcnt lgkmcnt(0)
	v_add_f32_e32 v3, v3, v5
	s_nop 1
	v_mov_b32_dpp v5, v3 row_mirror row_mask:0xf bank_mask:0xf
	s_waitcnt lgkmcnt(0)
	v_add_f32_e32 v3, v3, v5
	ds_bpermute_b32 v5, v69, v3
	s_waitcnt lgkmcnt(0)
; #define LAS __attribute__((address_space(3)))
; __device__ __forceinline__ unsigned cvtpk(float lo, float hi) { f32x2_t v = {lo, hi}; bf16x2_t b = __builtin_convertvector(v, bf16x2_t); return __builtin_bit_cast(unsigned, b); }
; __device__ __forceinline__ void attn_phase(LAS unsigned char* lds, const bf16_t* Z, const bf16_t* VT, bf16_t* Y, const float* subln, float lam, float lam_init, float M0, unsigned* ctr, LAS int* s_unit, int wid_s_) {
;     ...
;             for (int r = 0; r < 16; ++r) { const int qrow = (r & 3) + 8 * (r >> 2) + 4 * hh; const float a = __shfl(inv, qrow);
;                 float o[4]; float ss = 0.f;
; #pragma unroll
;                 for (int cb = 0; cb < 4; ++cb) { o[cb] = O[cb][r] * a - xch[(cb * 16 + r) * 64]; ss += o[cb] * o[cb]; }
;                 ss += __shfl_xor(ss, 1); ss += __shfl_xor(ss, 2); ss += __shfl_xor(ss, 4); ss += __shfl_xor(ss, 8); ss += __shfl_xor(ss, 16);
;                 const float rn = 1.0f / sqrtf(ss * (1.f / 128.f) + NORM_EPS);
;                 LAS bf16_t* st = (LAS bf16_t*)(lds + rg * 8192) + qrow * 128 + rr;
; #pragma unroll
;                 for (int cb = 0; cb < 4; ++cb) st[32 * cb] = (bf16_t)(cvtpk(o[cb] * rn * sw[cb], 0.f) & 0xffffu);
;             }
	v_add_f32_e32 v3, v3, v5
	v_fmamk_f32 v3, v3, 0x3c000000, v185
	v_cmp_gt_f32_e32 vcc, s36, v3
	v_mul_f32_e32 v5, 0x4f800000, v3
	s_nop 0
	v_cndmask_b32_e32 v3, v3, v5, vcc
	v_sqrt_f32_e32 v5, v3
	s_nop 0
	v_add_u32_e32 v6, -1, v5
	v_fma_f32 v7, -v6, v5, v3
	v_cmp_ge_f32_e64 s[2:3], 0, v7
	v_add_u32_e32 v7, 1, v5
	s_nop 0
	v_cndmask_b32_e64 v6, v5, v6, s[2:3]
	v_fma_f32 v5, -v7, v5, v3
	v_cmp_lt_f32_e64 s[2:3], 0, v5
	s_nop 1
	v_cndmask_b32_e64 v5, v6, v7, s[2:3]
	v_mul_f32_e32 v6, 0x37800000, v5
	v_cndmask_b32_e32 v5, v5, v6, vcc
	v_cmp_class_f32_e32 vcc, v3, v186
	s_nop 1
	v_cndmask_b32_e32 v3, v5, v3, vcc
	v_div_scale_f32 v5, s[2:3], v3, v3, 1.0
	v_rcp_f32_e32 v6, v5
	s_nop 0
	v_fma_f32 v7, -v5, v6, 1.0
	v_fmac_f32_e32 v6, v7, v6
	v_div_scale_f32 v7, vcc, 1.0, v3, 1.0
	v_mul_f32_e32 v16, v7, v6
	v_fma_f32 v17, -v5, v16, v7
	v_fmac_f32_e32 v16, v17, v6
	v_fma_f32 v5, -v5, v16, v7
	v_div_fmas_f32 v5, v5, v6, v16
	v_div_fixup_f32 v3, v5, v3, 1.0
	v_mul_f32_e32 v1, v1, v3
	v_mul_f32_e32 v1, v65, v1
	v_cvt_pk_bf16_f32 v1, v1, s0
	ds_write_b16 v248, v1
	v_mul_f32_e32 v1, v2, v3
	v_mul_f32_e32 v0, v0, v3
	v_mul_f32_e32 v1, v66, v1
	v_mul_f32_e32 v0, v68, v0
	v_cvt_pk_bf16_f32 v1, v1, s0
	v_cvt_pk_bf16_f32 v0, v0, s0
	ds_write_b16 v248, v1 offset:64
	v_mul_f32_e32 v1, v4, v3
	ds_write_b16 v248, v0 offset:192
	v_or_b32_e32 v0, 16, v216
	v_mul_f32_e32 v1, v67, v1
	v_or_b32_e32 v0, v191, v0
	v_cvt_pk_bf16_f32 v1, v1, s0
	v_lshlrev_b32_e32 v0, 2, v0
	ds_write_b16 v248, v1 offset:128
	ds_bpermute_b32 v16, v0, v64
	ds_read2st64_b32 v[0:1], v204 offset0:8 offset1:9
	ds_read2st64_b32 v[2:3], v204 offset0:24 offset1:25
	ds_read2st64_b32 v[4:5], v204 offset0:40 offset1:41
	ds_read2st64_b32 v[6:7], v204 offset0:56 offset1:57
	s_waitcnt lgkmcnt(3)
	v_fma_f32 v0, v40, v16, -v0
	s_waitcnt lgkmcnt(2)
	v_fma_f32 v2, v56, v16, -v2
	v_mul_f32_e32 v17, v2, v2
	v_fmac_f32_e32 v17, v0, v0
	s_waitcnt lgkmcnt(1)
	v_fma_f32 v4, v24, v16, -v4
	v_fmac_f32_e32 v17, v4, v4
	s_waitcnt lgkmcnt(0)
	v_fma_f32 v6, v8, v16, -v6
	v_fmac_f32_e32 v17, v6, v6
	s_nop 1
	v_mov_b32_dpp v8, v17 quad_perm:[1,0,3,2] row_mask:0xf bank_mask:0xf
	s_waitcnt lgkmcnt(0)
	v_add_f32_e32 v8, v17, v8
	s_nop 1
	v_mov_b32_dpp v16, v8 quad_perm:[2,3,0,1] row_mask:0xf bank_mask:0xf
	s_waitcnt lgkmcnt(0)
	v_add_f32_e32 v8, v8, v16
	s_nop 1
	v_mov_b32_dpp v16, v8 row_half_mirror row_mask:0xf bank_mask:0xf
	s_waitcnt lgkmcnt(0)
	v_add_f32_e32 v8, v8, v16
	s_nop 1
	v_mov_b32_dpp v16, v8 row_mirror row_mask:0xf bank_mask:0xf
	s_waitcnt lgkmcnt(0)
	v_add_f32_e32 v8, v8, v16
	ds_bpermute_b32 v16, v69, v8
	s_waitcnt lgkmcnt(0)
	v_add_f32_e32 v8, v8, v16
	v_fmamk_f32 v8, v8, 0x3c000000, v185
	v_cmp_gt_f32_e32 vcc, s36, v8
	v_mul_f32_e32 v16, 0x4f800000, v8
	s_nop 0
	v_cndmask_b32_e32 v8, v8, v16, vcc
	v_sqrt_f32_e32 v16, v8
	s_nop 0
	v_add_u32_e32 v17, -1, v16
	v_fma_f32 v18, -v17, v16, v8
	v_cmp_ge_f32_e64 s[2:3], 0, v18
	v_add_u32_e32 v18, 1, v16
	s_nop 0
	v_cndmask_b32_e64 v17, v16, v17, s[2:3]
	v_fma_f32 v16, -v18, v16, v8
	v_cmp_lt_f32_e64 s[2:3], 0, v16
	s_nop 1
	v_cndmask_b32_e64 v16, v17, v18, s[2:3]
	v_mul_f32_e32 v17, 0x37800000, v16
	v_cndmask_b32_e32 v16, v16, v17, vcc
	v_cmp_class_f32_e32 vcc, v8, v186
	s_nop 1
	v_cndmask_b32_e32 v8, v16, v8, vcc
	v_div_scale_f32 v16, s[2:3], v8, v8, 1.0
	v_rcp_f32_e32 v17, v16
	s_nop 0
	v_fma_f32 v18, -v16, v17, 1.0
	v_fmac_f32_e32 v17, v18, v17
	v_div_scale_f32 v18, vcc, 1.0, v8, 1.0
	v_mul_f32_e32 v19, v18, v17
	v_fma_f32 v20, -v16, v19, v18
	v_fmac_f32_e32 v19, v20, v17
	v_fma_f32 v16, -v16, v19, v18
	v_div_fmas_f32 v16, v16, v17, v19
	v_div_fixup_f32 v8, v16, v8, 1.0
	v_mul_f32_e32 v0, v0, v8
	v_mul_f32_e32 v0, v65, v0
	v_cvt_pk_bf16_f32 v0, v0, s0
	ds_write_b16 v249, v0
	v_mul_f32_e32 v0, v2, v8
	v_mul_f32_e32 v0, v66, v0
	v_cvt_pk_bf16_f32 v0, v0, s0
	ds_write_b16 v249, v0 offset:64
	v_mul_f32_e32 v0, v4, v8
	v_mul_f32_e32 v0, v67, v0
	v_cvt_pk_bf16_f32 v0, v0, s0
	ds_write_b16 v249, v0 offset:128
	v_mul_f32_e32 v0, v6, v8
	v_mul_f32_e32 v0, v68, v0
	v_cvt_pk_bf16_f32 v0, v0, s0
	ds_write_b16 v249, v0 offset:192
	v_or_b32_e32 v0, 17, v216
	v_or_b32_e32 v0, v191, v0
	v_lshlrev_b32_e32 v0, 2, v0
	ds_bpermute_b32 v0, v0, v64
	s_waitcnt lgkmcnt(0)
	v_fma_f32 v2, v57, v0, -v3
	v_fma_f32 v1, v41, v0, -v1
	v_mul_f32_e32 v3, v2, v2
	v_fmac_f32_e32 v3, v1, v1
	v_fma_f32 v4, v25, v0, -v5
	v_fmac_f32_e32 v3, v4, v4
	v_fma_f32 v0, v9, v0, -v7
	v_fmac_f32_e32 v3, v0, v0
	s_nop 1
	v_mov_b32_dpp v5, v3 quad_perm:[1,0,3,2] row_mask:0xf bank_mask:0xf
	s_waitcnt lgkmcnt(0)
	v_add_f32_e32 v3, v3, v5
	s_nop 1
	v_mov_b32_dpp v5, v3 quad_perm:[2,3,0,1] row_mask:0xf bank_mask:0xf
	s_waitcnt lgkmcnt(0)
	v_add_f32_e32 v3, v3, v5
	s_nop 1
	v_mov_b32_dpp v5, v3 row_half_mirror row_mask:0xf bank_mask:0xf
	s_waitcnt lgkmcnt(0)
	v_add_f32_e32 v3, v3, v5
	s_nop 1
	v_mov_b32_dpp v5, v3 row_mirror row_mask:0xf bank_mask:0xf
	s_waitcnt lgkmcnt(0)
	v_add_f32_e32 v3, v3, v5
	ds_bpermute_b32 v5, v69, v3
	s_waitcnt lgkmcnt(0)
; #define LAS __attribute__((address_space(3)))
; __device__ __forceinline__ unsigned cvtpk(float lo, float hi) { f32x2_t v = {lo, hi}; bf16x2_t b = __builtin_convertvector(v, bf16x2_t); return __builtin_bit_cast(unsigned, b); }
; __device__ __forceinline__ void attn_phase(LAS unsigned char* lds, const bf16_t* Z, const bf16_t* VT, bf16_t* Y, const float* subln, float lam, float lam_init, float M0, unsigned* ctr, LAS int* s_unit, int wid_s_) {
;     ...
;             for (int r = 0; r < 16; ++r) { const int qrow = (r & 3) + 8 * (r >> 2) + 4 * hh; const float a = __shfl(inv, qrow);
;                 float o[4]; float ss = 0.f;
; #pragma unroll
;                 for (int cb = 0; cb < 4; ++cb) { o[cb] = O[cb][r] * a - xch[(cb * 16 + r) * 64]; ss += o[cb] * o[cb]; }
;                 ss += __shfl_xor(ss, 1); ss += __shfl_xor(ss, 2); ss += __shfl_xor(ss, 4); ss += __shfl_xor(ss, 8); ss += __shfl_xor(ss, 16);
;                 const float rn = 1.0f / sqrtf(ss * (1.f / 128.f) + NORM_EPS);
;                 LAS bf16_t* st = (LAS bf16_t*)(lds + rg * 8192) + qrow * 128 + rr;
; #pragma unroll
;                 for (int cb = 0; cb < 4; ++cb) st[32 * cb] = (bf16_t)(cvtpk(o[cb] * rn * sw[cb], 0.f) & 0xffffu);
;             }
	v_add_f32_e32 v3, v3, v5
	v_fmamk_f32 v3, v3, 0x3c000000, v185
	v_cmp_gt_f32_e32 vcc, s36, v3
	v_mul_f32_e32 v5, 0x4f800000, v3
	s_nop 0
	v_cndmask_b32_e32 v3, v3, v5, vcc
	v_sqrt_f32_e32 v5, v3
	s_nop 0
	v_add_u32_e32 v6, -1, v5
	v_fma_f32 v7, -v6, v5, v3
	v_cmp_ge_f32_e64 s[2:3], 0, v7
	v_add_u32_e32 v7, 1, v5
	s_nop 0
	v_cndmask_b32_e64 v6, v5, v6, s[2:3]
	v_fma_f32 v5, -v7, v5, v3
	v_cmp_lt_f32_e64 s[2:3], 0, v5
	s_nop 1
	v_cndmask_b32_e64 v5, v6, v7, s[2:3]
	v_mul_f32_e32 v6, 0x37800000, v5
	v_cndmask_b32_e32 v5, v5, v6, vcc
	v_cmp_class_f32_e32 vcc, v3, v186
	s_nop 1
	v_cndmask_b32_e32 v3, v5, v3, vcc
	v_div_scale_f32 v5, s[2:3], v3, v3, 1.0
	v_rcp_f32_e32 v6, v5
	s_nop 0
	v_fma_f32 v7, -v5, v6, 1.0
	v_fmac_f32_e32 v6, v7, v6
	v_div_scale_f32 v7, vcc, 1.0, v3, 1.0
	v_mul_f32_e32 v8, v7, v6
	v_fma_f32 v9, -v5, v8, v7
	v_fmac_f32_e32 v8, v9, v6
	v_fma_f32 v5, -v5, v8, v7
	v_div_fmas_f32 v5, v5, v6, v8
	v_div_fixup_f32 v3, v5, v3, 1.0
	v_mul_f32_e32 v1, v1, v3
	v_mul_f32_e32 v0, v0, v3
	v_mul_f32_e32 v1, v65, v1
	v_mul_f32_e32 v0, v68, v0
	v_cvt_pk_bf16_f32 v1, v1, s0
	v_cvt_pk_bf16_f32 v0, v0, s0
	ds_write_b16 v250, v1
	v_mul_f32_e32 v1, v2, v3
	ds_write_b16 v250, v0 offset:192
	v_or_b32_e32 v0, 18, v216
	v_mul_f32_e32 v1, v66, v1
	v_or_b32_e32 v0, v191, v0
	v_cvt_pk_bf16_f32 v1, v1, s0
	v_lshlrev_b32_e32 v0, 2, v0
	ds_write_b16 v250, v1 offset:64
	v_mul_f32_e32 v1, v4, v3
	ds_bpermute_b32 v0, v0, v64
	ds_read2st64_b32 v[2:3], v204 offset0:10 offset1:11
	ds_read2st64_b32 v[4:5], v204 offset0:26 offset1:27
	ds_read2st64_b32 v[6:7], v204 offset0:42 offset1:43
	ds_read2st64_b32 v[8:9], v204 offset0:58 offset1:59
	v_mul_f32_e32 v1, v67, v1
	v_cvt_pk_bf16_f32 v1, v1, s0
	ds_write_b16 v250, v1 offset:128
	s_waitcnt lgkmcnt(4)
	v_fma_f32 v1, v42, v0, -v2
	s_waitcnt lgkmcnt(3)
	v_fma_f32 v2, v58, v0, -v4
	v_mul_f32_e32 v4, v2, v2
	v_fmac_f32_e32 v4, v1, v1
	s_waitcnt lgkmcnt(2)
	v_fma_f32 v6, v26, v0, -v6
	v_fmac_f32_e32 v4, v6, v6
	s_waitcnt lgkmcnt(1)
	v_fma_f32 v0, v10, v0, -v8
	v_fmac_f32_e32 v4, v0, v0
	s_nop 1
	v_mov_b32_dpp v8, v4 quad_perm:[1,0,3,2] row_mask:0xf bank_mask:0xf
	s_waitcnt lgkmcnt(0)
	v_add_f32_e32 v4, v4, v8
	s_nop 1
	v_mov_b32_dpp v8, v4 quad_perm:[2,3,0,1] row_mask:0xf bank_mask:0xf
	s_waitcnt lgkmcnt(0)
	v_add_f32_e32 v4, v4, v8
	s_nop 1
	v_mov_b32_dpp v8, v4 row_half_mirror row_mask:0xf bank_mask:0xf
	s_waitcnt lgkmcnt(0)
	v_add_f32_e32 v4, v4, v8
	s_nop 1
	v_mov_b32_dpp v8, v4 row_mirror row_mask:0xf bank_mask:0xf
	s_waitcnt lgkmcnt(0)
	v_add_f32_e32 v4, v4, v8
	ds_bpermute_b32 v8, v69, v4
	s_waitcnt lgkmcnt(0)
	v_add_f32_e32 v4, v4, v8
	v_fmamk_f32 v4, v4, 0x3c000000, v185
	v_cmp_gt_f32_e32 vcc, s36, v4
	v_mul_f32_e32 v8, 0x4f800000, v4
	s_nop 0
	v_cndmask_b32_e32 v4, v4, v8, vcc
	v_sqrt_f32_e32 v8, v4
	s_nop 0
	v_add_u32_e32 v10, -1, v8
	v_fma_f32 v16, -v10, v8, v4
	v_cmp_ge_f32_e64 s[2:3], 0, v16
	v_add_u32_e32 v16, 1, v8
	s_nop 0
	v_cndmask_b32_e64 v10, v8, v10, s[2:3]
	v_fma_f32 v8, -v16, v8, v4
	v_cmp_lt_f32_e64 s[2:3], 0, v8
	s_nop 1
	v_cndmask_b32_e64 v8, v10, v16, s[2:3]
	v_mul_f32_e32 v10, 0x37800000, v8
	v_cndmask_b32_e32 v8, v8, v10, vcc
	v_cmp_class_f32_e32 vcc, v4, v186
	s_nop 1
	v_cndmask_b32_e32 v4, v8, v4, vcc
	v_div_scale_f32 v8, s[2:3], v4, v4, 1.0
	v_rcp_f32_e32 v10, v8
	s_nop 0
	v_fma_f32 v16, -v8, v10, 1.0
	v_fmac_f32_e32 v10, v16, v10
	v_div_scale_f32 v16, vcc, 1.0, v4, 1.0
	v_mul_f32_e32 v17, v16, v10
	v_fma_f32 v18, -v8, v17, v16
	v_fmac_f32_e32 v17, v18, v10
	v_fma_f32 v8, -v8, v17, v16
	v_div_fmas_f32 v8, v8, v10, v17
	v_div_fixup_f32 v4, v8, v4, 1.0
	v_mul_f32_e32 v0, v0, v4
	v_mul_f32_e32 v0, v68, v0
	v_cvt_pk_bf16_f32 v0, v0, s0
	v_mul_f32_e32 v1, v1, v4
	ds_write_b16 v251, v0 offset:192
	v_or_b32_e32 v0, 19, v216
	v_mul_f32_e32 v1, v65, v1
	v_or_b32_e32 v0, v191, v0
	v_cvt_pk_bf16_f32 v1, v1, s0
	v_lshlrev_b32_e32 v0, 2, v0
	ds_write_b16 v251, v1
	v_mul_f32_e32 v1, v2, v4
	ds_bpermute_b32 v0, v0, v64
	v_mul_f32_e32 v1, v66, v1
	v_cvt_pk_bf16_f32 v1, v1, s0
	ds_write_b16 v251, v1 offset:64
	v_mul_f32_e32 v1, v6, v4
	v_mul_f32_e32 v1, v67, v1
	v_cvt_pk_bf16_f32 v1, v1, s0
	s_waitcnt lgkmcnt(1)
	v_fma_f32 v2, v59, v0, -v5
	ds_write_b16 v251, v1 offset:128
	v_fma_f32 v1, v43, v0, -v3
	v_mul_f32_e32 v3, v2, v2
	v_fmac_f32_e32 v3, v1, v1
	v_fma_f32 v4, v27, v0, -v7
	v_fmac_f32_e32 v3, v4, v4
	v_fma_f32 v0, v11, v0, -v9
	v_fmac_f32_e32 v3, v0, v0
	s_nop 1
	v_mov_b32_dpp v5, v3 quad_perm:[1,0,3,2] row_mask:0xf bank_mask:0xf
	s_waitcnt lgkmcnt(0)
	v_add_f32_e32 v3, v3, v5
	s_nop 1
	v_mov_b32_dpp v5, v3 quad_perm:[2,3,0,1] row_mask:0xf bank_mask:0xf
	s_waitcnt lgkmcnt(0)
	v_add_f32_e32 v3, v3, v5
	s_nop 1
	v_mov_b32_dpp v5, v3 row_half_mirror row_mask:0xf bank_mask:0xf
	s_waitcnt lgkmcnt(0)
	v_add_f32_e32 v3, v3, v5
	s_nop 1
	v_mov_b32_dpp v5, v3 row_mirror row_mask:0xf bank_mask:0xf
	s_waitcnt lgkmcnt(0)
	v_add_f32_e32 v3, v3, v5
	ds_bpermute_b32 v5, v69, v3
	s_waitcnt lgkmcnt(0)
; #define LAS __attribute__((address_space(3)))
; __device__ __forceinline__ unsigned cvtpk(float lo, float hi) { f32x2_t v = {lo, hi}; bf16x2_t b = __builtin_convertvector(v, bf16x2_t); return __builtin_bit_cast(unsigned, b); }
; __device__ __forceinline__ void attn_phase(LAS unsigned char* lds, const bf16_t* Z, const bf16_t* VT, bf16_t* Y, const float* subln, float lam, float lam_init, float M0, unsigned* ctr, LAS int* s_unit, int wid_s_) {
;     ...
;             for (int r = 0; r < 16; ++r) { const int qrow = (r & 3) + 8 * (r >> 2) + 4 * hh; const float a = __shfl(inv, qrow);
;                 float o[4]; float ss = 0.f;
; #pragma unroll
;                 for (int cb = 0; cb < 4; ++cb) { o[cb] = O[cb][r] * a - xch[(cb * 16 + r) * 64]; ss += o[cb] * o[cb]; }
;                 ss += __shfl_xor(ss, 1); ss += __shfl_xor(ss, 2); ss += __shfl_xor(ss, 4); ss += __shfl_xor(ss, 8); ss += __shfl_xor(ss, 16);
;                 const float rn = 1.0f / sqrtf(ss * (1.f / 128.f) + NORM_EPS);
;                 LAS bf16_t* st = (LAS bf16_t*)(lds + rg * 8192) + qrow * 128 + rr;
; #pragma unroll
;                 for (int cb = 0; cb < 4; ++cb) st[32 * cb] = (bf16_t)(cvtpk(o[cb] * rn * sw[cb], 0.f) & 0xffffu);
;             }
	v_add_f32_e32 v3, v3, v5
	v_fmamk_f32 v3, v3, 0x3c000000, v185
	v_cmp_gt_f32_e32 vcc, s36, v3
	v_mul_f32_e32 v5, 0x4f800000, v3
	s_nop 0
	v_cndmask_b32_e32 v3, v3, v5, vcc
	v_sqrt_f32_e32 v5, v3
	s_nop 0
	v_add_u32_e32 v6, -1, v5
	v_fma_f32 v7, -v6, v5, v3
	v_cmp_ge_f32_e64 s[2:3], 0, v7
	v_add_u32_e32 v7, 1, v5
	s_nop 0
	v_cndmask_b32_e64 v6, v5, v6, s[2:3]
	v_fma_f32 v5, -v7, v5, v3
	v_cmp_lt_f32_e64 s[2:3], 0, v5
	s_nop 1
	v_cndmask_b32_e64 v5, v6, v7, s[2:3]
	v_mul_f32_e32 v6, 0x37800000, v5
	v_cndmask_b32_e32 v5, v5, v6, vcc
	v_cmp_class_f32_e32 vcc, v3, v186
	s_nop 1
	v_cndmask_b32_e32 v3, v5, v3, vcc
	v_div_scale_f32 v5, s[2:3], v3, v3, 1.0
	v_rcp_f32_e32 v6, v5
	s_nop 0
	v_fma_f32 v7, -v5, v6, 1.0
	v_fmac_f32_e32 v6, v7, v6
	v_div_scale_f32 v7, vcc, 1.0, v3, 1.0
	v_mul_f32_e32 v8, v7, v6
	v_fma_f32 v9, -v5, v8, v7
	v_fmac_f32_e32 v8, v9, v6
	v_fma_f32 v5, -v5, v8, v7
	v_div_fmas_f32 v5, v5, v6, v8
	v_div_fixup_f32 v3, v5, v3, 1.0
	v_mul_f32_e32 v1, v1, v3
	v_mul_f32_e32 v0, v0, v3
	v_mul_f32_e32 v1, v65, v1
	v_mul_f32_e32 v0, v68, v0
	v_cvt_pk_bf16_f32 v1, v1, s0
	v_cvt_pk_bf16_f32 v0, v0, s0
	ds_write_b16 v252, v1
	v_mul_f32_e32 v1, v2, v3
	ds_write_b16 v252, v0 offset:192
	v_or_b32_e32 v0, 24, v216
	v_mul_f32_e32 v1, v66, v1
	v_or_b32_e32 v0, v191, v0
	v_cvt_pk_bf16_f32 v1, v1, s0
	v_lshlrev_b32_e32 v0, 2, v0
	ds_write_b16 v252, v1 offset:64
	v_mul_f32_e32 v1, v4, v3
	ds_bpermute_b32 v0, v0, v64
	ds_read2st64_b32 v[2:3], v204 offset0:12 offset1:13
	ds_read2st64_b32 v[4:5], v204 offset0:28 offset1:29
	ds_read2st64_b32 v[6:7], v204 offset0:44 offset1:45
	ds_read2st64_b32 v[8:9], v204 offset0:60 offset1:61
	v_mul_f32_e32 v1, v67, v1
	v_cvt_pk_bf16_f32 v1, v1, s0
	ds_write_b16 v252, v1 offset:128
	s_waitcnt lgkmcnt(4)
	v_fma_f32 v1, v44, v0, -v2
	s_waitcnt lgkmcnt(3)
	v_fma_f32 v2, v60, v0, -v4
	v_mul_f32_e32 v4, v2, v2
	v_fmac_f32_e32 v4, v1, v1
	s_waitcnt lgkmcnt(2)
	v_fma_f32 v6, v28, v0, -v6
	v_fmac_f32_e32 v4, v6, v6
	s_waitcnt lgkmcnt(1)
	v_fma_f32 v0, v12, v0, -v8
	v_fmac_f32_e32 v4, v0, v0
	s_nop 1
	v_mov_b32_dpp v8, v4 quad_perm:[1,0,3,2] row_mask:0xf bank_mask:0xf
	s_waitcnt lgkmcnt(0)
	v_add_f32_e32 v4, v4, v8
	s_nop 1
	v_mov_b32_dpp v8, v4 quad_perm:[2,3,0,1] row_mask:0xf bank_mask:0xf
	s_waitcnt lgkmcnt(0)
	v_add_f32_e32 v4, v4, v8
	s_nop 1
	v_mov_b32_dpp v8, v4 row_half_mirror row_mask:0xf bank_mask:0xf
	s_waitcnt lgkmcnt(0)
	v_add_f32_e32 v4, v4, v8
	s_nop 1
	v_mov_b32_dpp v8, v4 row_mirror row_mask:0xf bank_mask:0xf
	s_waitcnt lgkmcnt(0)
	v_add_f32_e32 v4, v4, v8
	ds_bpermute_b32 v8, v69, v4
	s_waitcnt lgkmcnt(0)
	v_add_f32_e32 v4, v4, v8
	v_fmamk_f32 v4, v4, 0x3c000000, v185
	v_cmp_gt_f32_e32 vcc, s36, v4
	v_mul_f32_e32 v8, 0x4f800000, v4
	s_nop 0
	v_cndmask_b32_e32 v4, v4, v8, vcc
	v_sqrt_f32_e32 v8, v4
	s_nop 0
	v_add_u32_e32 v10, -1, v8
	v_fma_f32 v11, -v10, v8, v4
	v_cmp_ge_f32_e64 s[2:3], 0, v11
	v_add_u32_e32 v11, 1, v8
	s_nop 0
	v_cndmask_b32_e64 v10, v8, v10, s[2:3]
	v_fma_f32 v8, -v11, v8, v4
	v_cmp_lt_f32_e64 s[2:3], 0, v8
	s_nop 1
	v_cndmask_b32_e64 v8, v10, v11, s[2:3]
	v_mul_f32_e32 v10, 0x37800000, v8
	v_cndmask_b32_e32 v8, v8, v10, vcc
	v_cmp_class_f32_e32 vcc, v4, v186
	s_nop 1
	v_cndmask_b32_e32 v4, v8, v4, vcc
	v_div_scale_f32 v8, s[2:3], v4, v4, 1.0
	v_rcp_f32_e32 v10, v8
	s_nop 0
	v_fma_f32 v11, -v8, v10, 1.0
	v_fmac_f32_e32 v10, v11, v10
	v_div_scale_f32 v11, vcc, 1.0, v4, 1.0
	v_mul_f32_e32 v12, v11, v10
	v_fma_f32 v16, -v8, v12, v11
	v_fmac_f32_e32 v12, v16, v10
	v_fma_f32 v8, -v8, v12, v11
	v_div_fmas_f32 v8, v8, v10, v12
	v_div_fixup_f32 v4, v8, v4, 1.0
	v_mul_f32_e32 v0, v0, v4
	v_mul_f32_e32 v0, v68, v0
	v_cvt_pk_bf16_f32 v0, v0, s0
	v_mul_f32_e32 v1, v1, v4
	ds_write_b16 v253, v0 offset:192
	v_or_b32_e32 v0, 25, v216
	v_mul_f32_e32 v1, v65, v1
	v_or_b32_e32 v0, v191, v0
	v_cvt_pk_bf16_f32 v1, v1, s0
	v_lshlrev_b32_e32 v0, 2, v0
	ds_write_b16 v253, v1
	v_mul_f32_e32 v1, v2, v4
	ds_bpermute_b32 v0, v0, v64
	v_mul_f32_e32 v1, v66, v1
	v_cvt_pk_bf16_f32 v1, v1, s0
	ds_write_b16 v253, v1 offset:64
	v_mul_f32_e32 v1, v6, v4
	v_mul_f32_e32 v1, v67, v1
	v_cvt_pk_bf16_f32 v1, v1, s0
	s_waitcnt lgkmcnt(1)
	v_fma_f32 v2, v61, v0, -v5
	ds_write_b16 v253, v1 offset:128
	v_fma_f32 v1, v45, v0, -v3
	v_mul_f32_e32 v3, v2, v2
	v_fmac_f32_e32 v3, v1, v1
	v_fma_f32 v4, v29, v0, -v7
	v_fmac_f32_e32 v3, v4, v4
	v_fma_f32 v0, v13, v0, -v9
	v_fmac_f32_e32 v3, v0, v0
	s_nop 1
	v_mov_b32_dpp v5, v3 quad_perm:[1,0,3,2] row_mask:0xf bank_mask:0xf
	s_waitcnt lgkmcnt(0)
	v_add_f32_e32 v3, v3, v5
	s_nop 1
	v_mov_b32_dpp v5, v3 quad_perm:[2,3,0,1] row_mask:0xf bank_mask:0xf
	s_waitcnt lgkmcnt(0)
	v_add_f32_e32 v3, v3, v5
	s_nop 1
	v_mov_b32_dpp v5, v3 row_half_mirror row_mask:0xf bank_mask:0xf
	s_waitcnt lgkmcnt(0)
	v_add_f32_e32 v3, v3, v5
	s_nop 1
	v_mov_b32_dpp v5, v3 row_mirror row_mask:0xf bank_mask:0xf
	s_waitcnt lgkmcnt(0)
	v_add_f32_e32 v3, v3, v5
	ds_bpermute_b32 v5, v69, v3
	s_waitcnt lgkmcnt(0)
; #define LAS __attribute__((address_space(3)))
; __device__ __forceinline__ unsigned cvtpk(float lo, float hi) { f32x2_t v = {lo, hi}; bf16x2_t b = __builtin_convertvector(v, bf16x2_t); return __builtin_bit_cast(unsigned, b); }
; __device__ __forceinline__ void attn_phase(LAS unsigned char* lds, const bf16_t* Z, const bf16_t* VT, bf16_t* Y, const float* subln, float lam, float lam_init, float M0, unsigned* ctr, LAS int* s_unit, int wid_s_) {
;     ...
;             for (int r = 0; r < 16; ++r) { const int qrow = (r & 3) + 8 * (r >> 2) + 4 * hh; const float a = __shfl(inv, qrow);
;                 float o[4]; float ss = 0.f;
; #pragma unroll
;                 for (int cb = 0; cb < 4; ++cb) { o[cb] = O[cb][r] * a - xch[(cb * 16 + r) * 64]; ss += o[cb] * o[cb]; }
;                 ss += __shfl_xor(ss, 1); ss += __shfl_xor(ss, 2); ss += __shfl_xor(ss, 4); ss += __shfl_xor(ss, 8); ss += __shfl_xor(ss, 16);
;                 const float rn = 1.0f / sqrtf(ss * (1.f / 128.f) + NORM_EPS);
;                 LAS bf16_t* st = (LAS bf16_t*)(lds + rg * 8192) + qrow * 128 + rr;
; #pragma unroll
;                 for (int cb = 0; cb < 4; ++cb) st[32 * cb] = (bf16_t)(cvtpk(o[cb] * rn * sw[cb], 0.f) & 0xffffu);
;             }
	v_add_f32_e32 v3, v3, v5
	v_fmamk_f32 v3, v3, 0x3c000000, v185
	v_cmp_gt_f32_e32 vcc, s36, v3
	v_mul_f32_e32 v5, 0x4f800000, v3
	s_nop 0
	v_cndmask_b32_e32 v3, v3, v5, vcc
	v_sqrt_f32_e32 v5, v3
	s_nop 0
	v_add_u32_e32 v6, -1, v5
	v_fma_f32 v7, -v6, v5, v3
	v_cmp_ge_f32_e64 s[2:3], 0, v7
	v_add_u32_e32 v7, 1, v5
	s_nop 0
	v_cndmask_b32_e64 v6, v5, v6, s[2:3]
	v_fma_f32 v5, -v7, v5, v3
	v_cmp_lt_f32_e64 s[2:3], 0, v5
	s_nop 1
	v_cndmask_b32_e64 v5, v6, v7, s[2:3]
	v_mul_f32_e32 v6, 0x37800000, v5
	v_cndmask_b32_e32 v5, v5, v6, vcc
	v_cmp_class_f32_e32 vcc, v3, v186
	s_nop 1
	v_cndmask_b32_e32 v3, v5, v3, vcc
	v_div_scale_f32 v5, s[2:3], v3, v3, 1.0
	v_rcp_f32_e32 v6, v5
	s_nop 0
	v_fma_f32 v7, -v5, v6, 1.0
	v_fmac_f32_e32 v6, v7, v6
	v_div_scale_f32 v7, vcc, 1.0, v3, 1.0
	v_mul_f32_e32 v8, v7, v6
	v_fma_f32 v9, -v5, v8, v7
	v_fmac_f32_e32 v8, v9, v6
	v_fma_f32 v5, -v5, v8, v7
	v_div_fmas_f32 v5, v5, v6, v8
	v_div_fixup_f32 v3, v5, v3, 1.0
	v_mul_f32_e32 v1, v1, v3
	v_mul_f32_e32 v1, v65, v1
	v_cvt_pk_bf16_f32 v1, v1, s0
	ds_write_b16 v187, v1
	v_mul_f32_e32 v1, v2, v3
	v_mul_f32_e32 v1, v66, v1
	v_mul_f32_e32 v0, v0, v3
	v_cvt_pk_bf16_f32 v1, v1, s0
	v_mul_f32_e32 v0, v68, v0
	ds_write_b16 v187, v1 offset:64
	v_mul_f32_e32 v1, v4, v3
	v_cvt_pk_bf16_f32 v0, v0, s0
	v_mul_f32_e32 v1, v67, v1
	ds_write_b16 v187, v0 offset:192
	v_or_b32_e32 v0, v191, v230
	v_cvt_pk_bf16_f32 v1, v1, s0
	v_lshlrev_b32_e32 v0, 2, v0
	ds_write_b16 v187, v1 offset:128
	ds_bpermute_b32 v8, v0, v64
	ds_read2st64_b32 v[0:1], v204 offset0:14 offset1:15
	ds_read2st64_b32 v[2:3], v204 offset0:30 offset1:31
	ds_read2st64_b32 v[4:5], v204 offset0:46 offset1:47
	ds_read2st64_b32 v[6:7], v204 offset0:62 offset1:63
	s_waitcnt lgkmcnt(3)
	v_fma_f32 v0, v46, v8, -v0
	s_waitcnt lgkmcnt(2)
	v_fma_f32 v2, v62, v8, -v2
	v_mul_f32_e32 v9, v2, v2
	v_fmac_f32_e32 v9, v0, v0
	s_waitcnt lgkmcnt(1)
	v_fma_f32 v4, v30, v8, -v4
	v_fmac_f32_e32 v9, v4, v4
	s_waitcnt lgkmcnt(0)
	v_fma_f32 v6, v14, v8, -v6
	v_fmac_f32_e32 v9, v6, v6
	s_nop 1
	v_mov_b32_dpp v8, v9 quad_perm:[1,0,3,2] row_mask:0xf bank_mask:0xf
	s_waitcnt lgkmcnt(0)
	v_add_f32_e32 v8, v9, v8
	s_nop 1
	v_mov_b32_dpp v9, v8 quad_perm:[2,3,0,1] row_mask:0xf bank_mask:0xf
	s_waitcnt lgkmcnt(0)
	v_add_f32_e32 v8, v8, v9
	s_nop 1
	v_mov_b32_dpp v9, v8 row_half_mirror row_mask:0xf bank_mask:0xf
	s_waitcnt lgkmcnt(0)
	v_add_f32_e32 v8, v8, v9
	s_nop 1
	v_mov_b32_dpp v9, v8 row_mirror row_mask:0xf bank_mask:0xf
	s_waitcnt lgkmcnt(0)
	v_add_f32_e32 v8, v8, v9
	ds_bpermute_b32 v9, v69, v8
	s_waitcnt lgkmcnt(0)
	v_add_f32_e32 v8, v8, v9
	v_fmamk_f32 v8, v8, 0x3c000000, v185
	v_cmp_gt_f32_e32 vcc, s36, v8
	v_mul_f32_e32 v9, 0x4f800000, v8
	s_nop 0
	v_cndmask_b32_e32 v8, v8, v9, vcc
	v_sqrt_f32_e32 v9, v8
	s_nop 0
	v_add_u32_e32 v10, -1, v9
	v_fma_f32 v11, -v10, v9, v8
	v_cmp_ge_f32_e64 s[2:3], 0, v11
	v_add_u32_e32 v11, 1, v9
	s_nop 0
	v_cndmask_b32_e64 v10, v9, v10, s[2:3]
	v_fma_f32 v9, -v11, v9, v8
	v_cmp_lt_f32_e64 s[2:3], 0, v9
	s_nop 1
	v_cndmask_b32_e64 v9, v10, v11, s[2:3]
	v_mul_f32_e32 v10, 0x37800000, v9
	v_cndmask_b32_e32 v9, v9, v10, vcc
	v_cmp_class_f32_e32 vcc, v8, v186
	s_nop 1
	v_cndmask_b32_e32 v8, v9, v8, vcc
	v_div_scale_f32 v9, s[2:3], v8, v8, 1.0
	v_rcp_f32_e32 v10, v9
	s_nop 0
	v_fma_f32 v11, -v9, v10, 1.0
	v_fmac_f32_e32 v10, v11, v10
	v_div_scale_f32 v11, vcc, 1.0, v8, 1.0
	v_mul_f32_e32 v12, v11, v10
	v_fma_f32 v13, -v9, v12, v11
	v_fmac_f32_e32 v12, v13, v10
	v_fma_f32 v9, -v9, v12, v11
	v_div_fmas_f32 v9, v9, v10, v12
	v_div_fixup_f32 v8, v9, v8, 1.0
	v_mul_f32_e32 v0, v0, v8
	v_mul_f32_e32 v0, v65, v0
	v_cvt_pk_bf16_f32 v0, v0, s0
	ds_write_b16 v200, v0
	v_mul_f32_e32 v0, v2, v8
	v_mul_f32_e32 v0, v66, v0
	v_cvt_pk_bf16_f32 v0, v0, s0
	ds_write_b16 v200, v0 offset:64
	v_mul_f32_e32 v0, v4, v8
	v_mul_f32_e32 v0, v67, v0
	v_cvt_pk_bf16_f32 v0, v0, s0
	ds_write_b16 v200, v0 offset:128
	v_mul_f32_e32 v0, v6, v8
	v_mul_f32_e32 v0, v68, v0
	v_cvt_pk_bf16_f32 v0, v0, s0
	ds_write_b16 v200, v0 offset:192
	v_or_b32_e32 v0, v191, v231
	v_lshlrev_b32_e32 v0, 2, v0
	ds_bpermute_b32 v0, v0, v64
	v_or_b32_e32 v10, s40, v232
	v_ashrrev_i32_e32 v11, 31, v10
	s_waitcnt lgkmcnt(0)
	v_fma_f32 v2, v63, v0, -v3
	v_fma_f32 v1, v47, v0, -v1
	v_mul_f32_e32 v3, v2, v2
	v_fmac_f32_e32 v3, v1, v1
	v_fma_f32 v4, v31, v0, -v5
	v_fmac_f32_e32 v3, v4, v4
	v_fma_f32 v0, v15, v0, -v7
	v_fmac_f32_e32 v3, v0, v0
	s_nop 1
	v_mov_b32_dpp v5, v3 quad_perm:[1,0,3,2] row_mask:0xf bank_mask:0xf
	s_waitcnt lgkmcnt(0)
	v_add_f32_e32 v3, v3, v5
	s_nop 1
	v_mov_b32_dpp v5, v3 quad_perm:[2,3,0,1] row_mask:0xf bank_mask:0xf
	s_waitcnt lgkmcnt(0)
	v_add_f32_e32 v3, v3, v5
	s_nop 1
	v_mov_b32_dpp v5, v3 row_half_mirror row_mask:0xf bank_mask:0xf
	s_waitcnt lgkmcnt(0)
	v_add_f32_e32 v3, v3, v5
	s_nop 1
	v_mov_b32_dpp v5, v3 row_mirror row_mask:0xf bank_mask:0xf
	s_waitcnt lgkmcnt(0)
	v_add_f32_e32 v3, v3, v5
	ds_bpermute_b32 v5, v69, v3
	s_waitcnt lgkmcnt(0)
; #define LAS __attribute__((address_space(3)))
; __device__ __forceinline__ float bflo(unsigned w) { return __uint_as_float(w << 16); }
; __device__ __forceinline__ float bfhi(unsigned w) { return __uint_as_float(w & 0xffff0000u); }
; __device__ __forceinline__ unsigned cvtpk(float lo, float hi) { f32x2_t v = {lo, hi}; bf16x2_t b = __builtin_convertvector(v, bf16x2_t); return __builtin_bit_cast(unsigned, b); }
; __device__ __forceinline__ void attn_phase(LAS unsigned char* lds, const bf16_t* Z, const bf16_t* VT, bf16_t* Y, const float* subln, float lam, float lam_init, float M0, unsigned* ctr, LAS int* s_unit, int wid_s_) {
;     ...
;             for (int r = 0; r < 16; ++r) { const int qrow = (r & 3) + 8 * (r >> 2) + 4 * hh; const float a = __shfl(inv, qrow);
;                 float o[4]; float ss = 0.f;
; #pragma unroll
;                 for (int cb = 0; cb < 4; ++cb) { o[cb] = O[cb][r] * a - xch[(cb * 16 + r) * 64]; ss += o[cb] * o[cb]; }
;                 ss += __shfl_xor(ss, 1); ss += __shfl_xor(ss, 2); ss += __shfl_xor(ss, 4); ss += __shfl_xor(ss, 8); ss += __shfl_xor(ss, 16);
;                 const float rn = 1.0f / sqrtf(ss * (1.f / 128.f) + NORM_EPS);
;                 LAS bf16_t* st = (LAS bf16_t*)(lds + rg * 8192) + qrow * 128 + rr;
; #pragma unroll
;                 for (int cb = 0; cb < 4; ++cb) st[32 * cb] = (bf16_t)(cvtpk(o[cb] * rn * sw[cb], 0.f) & 0xffffu);
;             }
;             asm volatile("s_waitcnt lgkmcnt(0)" ::: "memory");
; #pragma unroll
;             for (int i = 0; i < 8; ++i) { const int c = i * 64 + lane, row = c >> 4, ch = c & 15; const size_t tok = (size_t)(qw + row);
;                 const u32x4 v = *(const LAS u32x4*)(lds + rg * 8192 + row * 256 + ch * 16);
;                 const u32x4 sg = *(const u32x4*)(Z + tok * ZP + 4096 + h * 128 + ch * 8);
;                 u32x4 w; w.x = cvtpk(bflo(v.x) * bflo(sg.x), bfhi(v.x) * bfhi(sg.x)); w.y = cvtpk(bflo(v.y) * bflo(sg.y), bfhi(v.y) * bfhi(sg.y));
;                 w.z = cvtpk(bflo(v.z) * bflo(sg.z), bfhi(v.z) * bfhi(sg.z)); w.w = cvtpk(bflo(v.w) * bflo(sg.w), bfhi(v.w) * bfhi(sg.w));
;                 *(u32x4*)(Y + tok * D + 1024 + h * 128 + ch * 8) = w; }
	v_add_f32_e32 v3, v3, v5
	v_fmamk_f32 v3, v3, 0x3c000000, v185
	v_cmp_gt_f32_e32 vcc, s36, v3
	v_mul_f32_e32 v5, 0x4f800000, v3
	s_nop 0
	v_cndmask_b32_e32 v3, v3, v5, vcc
	v_sqrt_f32_e32 v5, v3
	s_nop 0
	v_add_u32_e32 v6, -1, v5
	v_fma_f32 v7, -v6, v5, v3
	v_cmp_ge_f32_e64 s[2:3], 0, v7
	v_add_u32_e32 v7, 1, v5
	s_nop 0
	v_cndmask_b32_e64 v6, v5, v6, s[2:3]
	v_fma_f32 v5, -v7, v5, v3
	v_cmp_lt_f32_e64 s[2:3], 0, v5
	s_nop 1
	v_cndmask_b32_e64 v5, v6, v7, s[2:3]
	v_mul_f32_e32 v6, 0x37800000, v5
	v_cndmask_b32_e32 v5, v5, v6, vcc
	v_cmp_class_f32_e32 vcc, v3, v186
	s_nop 1
	v_cndmask_b32_e32 v3, v5, v3, vcc
	v_div_scale_f32 v5, s[2:3], v3, v3, 1.0
	v_rcp_f32_e32 v6, v5
	s_nop 0
	v_fma_f32 v7, -v5, v6, 1.0
	v_fmac_f32_e32 v6, v7, v6
	v_div_scale_f32 v7, vcc, 1.0, v3, 1.0
	v_mul_f32_e32 v8, v7, v6
	v_fma_f32 v9, -v5, v8, v7
	v_fmac_f32_e32 v8, v9, v6
	v_fma_f32 v5, -v5, v8, v7
	v_div_fmas_f32 v5, v5, v6, v8
	v_div_fixup_f32 v3, v5, v3, 1.0
	v_mul_f32_e32 v1, v1, v3
	v_mul_f32_e32 v1, v65, v1
	v_cvt_pk_bf16_f32 v1, v1, s0
	ds_write_b16 v188, v1
	v_mul_f32_e32 v1, v2, v3
	v_mul_f32_e32 v1, v66, v1
	v_cvt_pk_bf16_f32 v1, v1, s0
	ds_write_b16 v188, v1 offset:64
	v_mul_f32_e32 v1, v4, v3
	v_mul_f32_e32 v0, v0, v3
	v_mul_f32_e32 v1, v67, v1
	v_mul_f32_e32 v0, v68, v0
	v_cvt_pk_bf16_f32 v1, v1, s0
	v_cvt_pk_bf16_f32 v0, v0, s0
	ds_write_b16 v188, v1 offset:128
	ds_write_b16 v188, v0 offset:192
	v_mov_b64_e32 v[0:1], s[78:79]
	v_mad_i64_i32 v[6:7], s[2:3], v10, s33, v[0:1]
	v_lshl_add_u64 v[6:7], v[6:7], 0, s[26:27]
	v_lshl_add_u64 v[6:7], v[6:7], 0, v[170:171]
	v_add_co_u32_e32 v6, vcc, s15, v6
	s_waitcnt lgkmcnt(0)
	ds_read_b128 v[2:5], v150
	s_nop 0
	v_addc_co_u32_e32 v7, vcc, 0, v7, vcc
	flat_load_dwordx4 v[6:9], v[6:7]
	s_waitcnt lgkmcnt(0)
	v_lshlrev_b32_e32 v12, 16, v2
	v_and_b32_e32 v13, 0xffff0000, v2
	s_waitcnt vmcnt(0)
	v_lshlrev_b32_e32 v14, 16, v6
	v_and_b32_e32 v15, 0xffff0000, v6
	v_pk_mul_f32 v[12:13], v[12:13], v[14:15]
	v_lshlrev_b32_e32 v6, 16, v7
	v_cvt_pk_bf16_f32 v2, v12, v13
	v_lshlrev_b32_e32 v12, 16, v3
	v_and_b32_e32 v13, 0xffff0000, v3
	v_and_b32_e32 v7, 0xffff0000, v7
	v_pk_mul_f32 v[6:7], v[12:13], v[6:7]
	v_lshlrev_b32_e32 v12, 16, v8
	v_cvt_pk_bf16_f32 v3, v6, v7
	v_lshlrev_b32_e32 v6, 16, v4
	v_and_b32_e32 v7, 0xffff0000, v4
	v_and_b32_e32 v13, 0xffff0000, v8
	v_pk_mul_f32 v[6:7], v[6:7], v[12:13]
	v_lshlrev_b32_e32 v8, 16, v9
	v_cvt_pk_bf16_f32 v4, v6, v7
	v_lshlrev_b32_e32 v6, 16, v5
	v_and_b32_e32 v7, 0xffff0000, v5
	v_and_b32_e32 v9, 0xffff0000, v9
	v_pk_mul_f32 v[6:7], v[6:7], v[8:9]
	s_nop 0
	v_cvt_pk_bf16_f32 v5, v6, v7
	v_lshlrev_b64 v[6:7], 12, v[10:11]
	v_lshl_add_u64 v[6:7], s[4:5], 0, v[6:7]
	v_lshl_add_u64 v[6:7], v[6:7], 0, s[26:27]
	v_lshl_add_u64 v[6:7], v[6:7], 0, v[170:171]
	v_or_b32_e32 v10, s40, v233
	flat_store_dwordx4 v[6:7], v[2:5] offset:2048
	v_mad_i64_i32 v[6:7], s[2:3], v10, s33, v[0:1]
	v_lshl_add_u64 v[6:7], v[6:7], 0, s[26:27]
	v_lshl_add_u64 v[6:7], v[6:7], 0, v[170:171]
	v_add_co_u32_e32 v6, vcc, s15, v6
	ds_read_b128 v[2:5], v151
	s_nop 0
	v_addc_co_u32_e32 v7, vcc, 0, v7, vcc
	flat_load_dwordx4 v[6:9], v[6:7]
	v_ashrrev_i32_e32 v11, 31, v10
	s_waitcnt lgkmcnt(0)
	v_lshlrev_b32_e32 v12, 16, v2
	v_and_b32_e32 v13, 0xffff0000, v2
	s_waitcnt vmcnt(0)
	v_lshlrev_b32_e32 v14, 16, v6
	v_and_b32_e32 v15, 0xffff0000, v6
	v_pk_mul_f32 v[12:13], v[12:13], v[14:15]
	v_lshlrev_b32_e32 v6, 16, v7
	v_cvt_pk_bf16_f32 v2, v12, v13
	v_lshlrev_b32_e32 v12, 16, v3
	v_and_b32_e32 v13, 0xffff0000, v3
	v_and_b32_e32 v7, 0xffff0000, v7
	v_pk_mul_f32 v[6:7], v[12:13], v[6:7]
	v_lshlrev_b32_e32 v12, 16, v8
	v_cvt_pk_bf16_f32 v3, v6, v7
	v_lshlrev_b32_e32 v6, 16, v4
	v_and_b32_e32 v7, 0xffff0000, v4
	v_and_b32_e32 v13, 0xffff0000, v8
	v_pk_mul_f32 v[6:7], v[6:7], v[12:13]
	v_lshlrev_b32_e32 v8, 16, v9
	v_cvt_pk_bf16_f32 v4, v6, v7
	v_lshlrev_b32_e32 v6, 16, v5
	v_and_b32_e32 v7, 0xffff0000, v5
	v_and_b32_e32 v9, 0xffff0000, v9
	v_pk_mul_f32 v[6:7], v[6:7], v[8:9]
	s_nop 0
	v_cvt_pk_bf16_f32 v5, v6, v7
	v_lshlrev_b64 v[6:7], 12, v[10:11]
	v_lshl_add_u64 v[6:7], s[4:5], 0, v[6:7]
	v_lshl_add_u64 v[6:7], v[6:7], 0, s[26:27]
	v_lshl_add_u64 v[6:7], v[6:7], 0, v[170:171]
	v_or_b32_e32 v10, s40, v234
	flat_store_dwordx4 v[6:7], v[2:5] offset:2048
	v_mad_i64_i32 v[6:7], s[2:3], v10, s33, v[0:1]
	v_lshl_add_u64 v[6:7], v[6:7], 0, s[26:27]
	v_lshl_add_u64 v[6:7], v[6:7], 0, v[170:171]
	v_add_co_u32_e32 v6, vcc, s15, v6
	ds_read_b128 v[2:5], v199
	s_nop 0
	v_addc_co_u32_e32 v7, vcc, 0, v7, vcc
	flat_load_dwordx4 v[6:9], v[6:7]
	v_ashrrev_i32_e32 v11, 31, v10
	s_waitcnt lgkmcnt(0)
	v_lshlrev_b32_e32 v12, 16, v2
	v_and_b32_e32 v13, 0xffff0000, v2
	s_waitcnt vmcnt(0)
	v_lshlrev_b32_e32 v14, 16, v6
	v_and_b32_e32 v15, 0xffff0000, v6
	v_pk_mul_f32 v[12:13], v[12:13], v[14:15]
	v_lshlrev_b32_e32 v6, 16, v7
	v_cvt_pk_bf16_f32 v2, v12, v13
	v_lshlrev_b32_e32 v12, 16, v3
	v_and_b32_e32 v13, 0xffff0000, v3
	v_and_b32_e32 v7, 0xffff0000, v7
	v_pk_mul_f32 v[6:7], v[12:13], v[6:7]
	v_lshlrev_b32_e32 v12, 16, v8
	v_cvt_pk_bf16_f32 v3, v6, v7
	v_lshlrev_b32_e32 v6, 16, v4
	v_and_b32_e32 v7, 0xffff0000, v4
	v_and_b32_e32 v13, 0xffff0000, v8
	v_pk_mul_f32 v[6:7], v[6:7], v[12:13]
	v_lshlrev_b32_e32 v8, 16, v9
	v_cvt_pk_bf16_f32 v4, v6, v7
	v_lshlrev_b32_e32 v6, 16, v5
	v_and_b32_e32 v7, 0xffff0000, v5
	v_and_b32_e32 v9, 0xffff0000, v9
	v_pk_mul_f32 v[6:7], v[6:7], v[8:9]
	s_nop 0
	v_cvt_pk_bf16_f32 v5, v6, v7
	v_lshlrev_b64 v[6:7], 12, v[10:11]
	v_lshl_add_u64 v[6:7], s[4:5], 0, v[6:7]
	v_lshl_add_u64 v[6:7], v[6:7], 0, s[26:27]
	v_lshl_add_u64 v[6:7], v[6:7], 0, v[170:171]
	v_or_b32_e32 v10, s40, v235
	flat_store_dwordx4 v[6:7], v[2:5] offset:2048
	v_mad_i64_i32 v[6:7], s[2:3], v10, s33, v[0:1]
	v_lshl_add_u64 v[6:7], v[6:7], 0, s[26:27]
	v_lshl_add_u64 v[6:7], v[6:7], 0, v[170:171]
	v_add_co_u32_e32 v6, vcc, s15, v6
	ds_read_b128 v[2:5], v148
	s_nop 0
	v_addc_co_u32_e32 v7, vcc, 0, v7, vcc
	flat_load_dwordx4 v[6:9], v[6:7]
	v_ashrrev_i32_e32 v11, 31, v10
	s_waitcnt lgkmcnt(0)
; #define LAS __attribute__((address_space(3)))
; __device__ __forceinline__ float bflo(unsigned w) { return __uint_as_float(w << 16); }
; __device__ __forceinline__ float bfhi(unsigned w) { return __uint_as_float(w & 0xffff0000u); }
; __device__ __forceinline__ unsigned cvtpk(float lo, float hi) { f32x2_t v = {lo, hi}; bf16x2_t b = __builtin_convertvector(v, bf16x2_t); return __builtin_bit_cast(unsigned, b); }
; __device__ __forceinline__ void attn_phase(LAS unsigned char* lds, const bf16_t* Z, const bf16_t* VT, bf16_t* Y, const float* subln, float lam, float lam_init, float M0, unsigned* ctr, LAS int* s_unit, int wid_s_) {
;     ...
; #pragma unroll
;             for (int i = 0; i < 8; ++i) { const int c = i * 64 + lane, row = c >> 4, ch = c & 15; const size_t tok = (size_t)(qw + row);
;                 const u32x4 v = *(const LAS u32x4*)(lds + rg * 8192 + row * 256 + ch * 16);
;                 const u32x4 sg = *(const u32x4*)(Z + tok * ZP + 4096 + h * 128 + ch * 8);
;                 u32x4 w; w.x = cvtpk(bflo(v.x) * bflo(sg.x), bfhi(v.x) * bfhi(sg.x)); w.y = cvtpk(bflo(v.y) * bflo(sg.y), bfhi(v.y) * bfhi(sg.y));
;                 w.z = cvtpk(bflo(v.z) * bflo(sg.z), bfhi(v.z) * bfhi(sg.z)); w.w = cvtpk(bflo(v.w) * bflo(sg.w), bfhi(v.w) * bfhi(sg.w));
;                 *(u32x4*)(Y + tok * D + 1024 + h * 128 + ch * 8) = w; }
	v_lshlrev_b32_e32 v12, 16, v2
	v_and_b32_e32 v13, 0xffff0000, v2
	s_waitcnt vmcnt(0)
	v_lshlrev_b32_e32 v14, 16, v6
	v_and_b32_e32 v15, 0xffff0000, v6
	v_pk_mul_f32 v[12:13], v[12:13], v[14:15]
	v_lshlrev_b32_e32 v6, 16, v7
	v_cvt_pk_bf16_f32 v2, v12, v13
	v_lshlrev_b32_e32 v12, 16, v3
	v_and_b32_e32 v13, 0xffff0000, v3
	v_and_b32_e32 v7, 0xffff0000, v7
	v_pk_mul_f32 v[6:7], v[12:13], v[6:7]
	v_lshlrev_b32_e32 v12, 16, v8
	v_cvt_pk_bf16_f32 v3, v6, v7
	v_lshlrev_b32_e32 v6, 16, v4
	v_and_b32_e32 v7, 0xffff0000, v4
	v_and_b32_e32 v13, 0xffff0000, v8
	v_pk_mul_f32 v[6:7], v[6:7], v[12:13]
	v_lshlrev_b32_e32 v8, 16, v9
	v_cvt_pk_bf16_f32 v4, v6, v7
	v_lshlrev_b32_e32 v6, 16, v5
	v_and_b32_e32 v7, 0xffff0000, v5
	v_and_b32_e32 v9, 0xffff0000, v9
	v_pk_mul_f32 v[6:7], v[6:7], v[8:9]
	s_nop 0
	v_cvt_pk_bf16_f32 v5, v6, v7
	v_lshlrev_b64 v[6:7], 12, v[10:11]
	v_lshl_add_u64 v[6:7], s[4:5], 0, v[6:7]
	v_lshl_add_u64 v[6:7], v[6:7], 0, s[26:27]
	v_lshl_add_u64 v[6:7], v[6:7], 0, v[170:171]
	v_or_b32_e32 v10, s40, v236
	flat_store_dwordx4 v[6:7], v[2:5] offset:2048
	v_mad_i64_i32 v[6:7], s[2:3], v10, s33, v[0:1]
	v_lshl_add_u64 v[6:7], v[6:7], 0, s[26:27]
	v_lshl_add_u64 v[6:7], v[6:7], 0, v[170:171]
	v_add_co_u32_e32 v6, vcc, s15, v6
	ds_read_b128 v[2:5], v149
	s_nop 0
	v_addc_co_u32_e32 v7, vcc, 0, v7, vcc
	flat_load_dwordx4 v[6:9], v[6:7]
	v_ashrrev_i32_e32 v11, 31, v10
	s_waitcnt lgkmcnt(0)
	v_lshlrev_b32_e32 v12, 16, v2
	v_and_b32_e32 v13, 0xffff0000, v2
	s_waitcnt vmcnt(0)
	v_lshlrev_b32_e32 v14, 16, v6
	v_and_b32_e32 v15, 0xffff0000, v6
	v_pk_mul_f32 v[12:13], v[12:13], v[14:15]
	v_lshlrev_b32_e32 v6, 16, v7
	v_cvt_pk_bf16_f32 v2, v12, v13
	v_lshlrev_b32_e32 v12, 16, v3
	v_and_b32_e32 v13, 0xffff0000, v3
	v_and_b32_e32 v7, 0xffff0000, v7
	v_pk_mul_f32 v[6:7], v[12:13], v[6:7]
	v_lshlrev_b32_e32 v12, 16, v8
	v_cvt_pk_bf16_f32 v3, v6, v7
	v_lshlrev_b32_e32 v6, 16, v4
	v_and_b32_e32 v7, 0xffff0000, v4
	v_and_b32_e32 v13, 0xffff0000, v8
	v_pk_mul_f32 v[6:7], v[6:7], v[12:13]
	v_lshlrev_b32_e32 v8, 16, v9
	v_cvt_pk_bf16_f32 v4, v6, v7
	v_lshlrev_b32_e32 v6, 16, v5
	v_and_b32_e32 v7, 0xffff0000, v5
	v_and_b32_e32 v9, 0xffff0000, v9
	v_pk_mul_f32 v[6:7], v[6:7], v[8:9]
	s_nop 0
	v_cvt_pk_bf16_f32 v5, v6, v7
	v_lshlrev_b64 v[6:7], 12, v[10:11]
	v_lshl_add_u64 v[6:7], s[4:5], 0, v[6:7]
	v_lshl_add_u64 v[6:7], v[6:7], 0, s[26:27]
	v_lshl_add_u64 v[6:7], v[6:7], 0, v[170:171]
	v_or_b32_e32 v10, s40, v237
	flat_store_dwordx4 v[6:7], v[2:5] offset:2048
	v_mad_i64_i32 v[6:7], s[2:3], v10, s33, v[0:1]
	v_lshl_add_u64 v[6:7], v[6:7], 0, s[26:27]
	v_lshl_add_u64 v[6:7], v[6:7], 0, v[170:171]
	v_add_co_u32_e32 v6, vcc, s15, v6
	ds_read_b128 v[2:5], v146
	s_nop 0
	v_addc_co_u32_e32 v7, vcc, 0, v7, vcc
	flat_load_dwordx4 v[6:9], v[6:7]
	v_ashrrev_i32_e32 v11, 31, v10
	s_waitcnt lgkmcnt(0)
	v_lshlrev_b32_e32 v12, 16, v2
	v_and_b32_e32 v13, 0xffff0000, v2
	s_waitcnt vmcnt(0)
	v_lshlrev_b32_e32 v14, 16, v6
	v_and_b32_e32 v15, 0xffff0000, v6
	v_pk_mul_f32 v[12:13], v[12:13], v[14:15]
	v_lshlrev_b32_e32 v6, 16, v7
	v_cvt_pk_bf16_f32 v2, v12, v13
	v_lshlrev_b32_e32 v12, 16, v3
	v_and_b32_e32 v13, 0xffff0000, v3
	v_and_b32_e32 v7, 0xffff0000, v7
	v_pk_mul_f32 v[6:7], v[12:13], v[6:7]
	v_lshlrev_b32_e32 v12, 16, v8
	v_cvt_pk_bf16_f32 v3, v6, v7
	v_lshlrev_b32_e32 v6, 16, v4
	v_and_b32_e32 v7, 0xffff0000, v4
	v_and_b32_e32 v13, 0xffff0000, v8
	v_pk_mul_f32 v[6:7], v[6:7], v[12:13]
	v_lshlrev_b32_e32 v8, 16, v9
	v_cvt_pk_bf16_f32 v4, v6, v7
	v_lshlrev_b32_e32 v6, 16, v5
	v_and_b32_e32 v7, 0xffff0000, v5
	v_and_b32_e32 v9, 0xffff0000, v9
	v_pk_mul_f32 v[6:7], v[6:7], v[8:9]
	s_nop 0
	v_cvt_pk_bf16_f32 v5, v6, v7
	v_lshlrev_b64 v[6:7], 12, v[10:11]
	v_lshl_add_u64 v[6:7], s[4:5], 0, v[6:7]
	v_lshl_add_u64 v[6:7], v[6:7], 0, s[26:27]
	v_lshl_add_u64 v[6:7], v[6:7], 0, v[170:171]
	v_or_b32_e32 v10, s40, v238
	flat_store_dwordx4 v[6:7], v[2:5] offset:2048
	v_mad_i64_i32 v[6:7], s[2:3], v10, s33, v[0:1]
	v_lshl_add_u64 v[6:7], v[6:7], 0, s[26:27]
	v_lshl_add_u64 v[6:7], v[6:7], 0, v[170:171]
	v_add_co_u32_e32 v6, vcc, s15, v6
	ds_read_b128 v[2:5], v147
	s_nop 0
	v_addc_co_u32_e32 v7, vcc, 0, v7, vcc
	flat_load_dwordx4 v[6:9], v[6:7]
	v_ashrrev_i32_e32 v11, 31, v10
	s_waitcnt lgkmcnt(0)
	v_lshlrev_b32_e32 v12, 16, v2
	v_and_b32_e32 v13, 0xffff0000, v2
	s_waitcnt vmcnt(0)
	v_lshlrev_b32_e32 v14, 16, v6
	v_and_b32_e32 v15, 0xffff0000, v6
	v_pk_mul_f32 v[12:13], v[12:13], v[14:15]
	v_lshlrev_b32_e32 v6, 16, v7
	v_cvt_pk_bf16_f32 v2, v12, v13
	v_lshlrev_b32_e32 v12, 16, v3
	v_and_b32_e32 v13, 0xffff0000, v3
	v_and_b32_e32 v7, 0xffff0000, v7
	v_pk_mul_f32 v[6:7], v[12:13], v[6:7]
	v_lshlrev_b32_e32 v12, 16, v8
	v_cvt_pk_bf16_f32 v3, v6, v7
	v_lshlrev_b32_e32 v6, 16, v4
	v_and_b32_e32 v7, 0xffff0000, v4
	v_and_b32_e32 v13, 0xffff0000, v8
	v_pk_mul_f32 v[6:7], v[6:7], v[12:13]
	v_lshlrev_b32_e32 v8, 16, v9
	v_cvt_pk_bf16_f32 v4, v6, v7
	v_lshlrev_b32_e32 v6, 16, v5
	v_and_b32_e32 v7, 0xffff0000, v5
	v_and_b32_e32 v9, 0xffff0000, v9
	v_pk_mul_f32 v[6:7], v[6:7], v[8:9]
	s_nop 0
	v_cvt_pk_bf16_f32 v5, v6, v7
	v_lshlrev_b64 v[6:7], 12, v[10:11]
	v_or_b32_e32 v10, s40, v239
	v_mad_i64_i32 v[0:1], s[2:3], v10, s33, v[0:1]
	v_lshl_add_u64 v[6:7], s[4:5], 0, v[6:7]
	v_lshl_add_u64 v[0:1], v[0:1], 0, s[26:27]
	v_lshl_add_u64 v[6:7], v[6:7], 0, s[26:27]
	v_lshl_add_u64 v[0:1], v[0:1], 0, v[170:171]
	v_lshl_add_u64 v[6:7], v[6:7], 0, v[170:171]
	v_add_co_u32_e32 v0, vcc, s15, v0
	flat_store_dwordx4 v[6:7], v[2:5] offset:2048
	s_nop 0
	v_addc_co_u32_e32 v1, vcc, 0, v1, vcc
	flat_load_dwordx4 v[6:9], v[0:1]
	ds_read_b128 v[2:5], v196
	v_ashrrev_i32_e32 v11, 31, v10
	s_waitcnt lgkmcnt(0)
	v_lshlrev_b32_e32 v0, 16, v2
	v_and_b32_e32 v1, 0xffff0000, v2
	v_lshlrev_b32_e32 v2, 16, v3
	v_and_b32_e32 v3, 0xffff0000, v3
	s_waitcnt vmcnt(0)
	v_lshlrev_b32_e32 v12, 16, v6
	v_and_b32_e32 v13, 0xffff0000, v6
	v_lshlrev_b32_e32 v6, 16, v7
	v_and_b32_e32 v7, 0xffff0000, v7
	v_pk_mul_f32 v[0:1], v[0:1], v[12:13]
	v_pk_mul_f32 v[2:3], v[2:3], v[6:7]
	v_cvt_pk_bf16_f32 v0, v0, v1
	v_cvt_pk_bf16_f32 v1, v2, v3
	v_lshlrev_b32_e32 v2, 16, v4
	v_and_b32_e32 v3, 0xffff0000, v4
	v_lshlrev_b32_e32 v6, 16, v8
	v_and_b32_e32 v7, 0xffff0000, v8
	v_pk_mul_f32 v[2:3], v[2:3], v[6:7]
	v_lshlrev_b32_e32 v4, 16, v5
	v_and_b32_e32 v5, 0xffff0000, v5
	v_lshlrev_b32_e32 v6, 16, v9
	v_and_b32_e32 v7, 0xffff0000, v9
	v_pk_mul_f32 v[4:5], v[4:5], v[6:7]
	v_cvt_pk_bf16_f32 v2, v2, v3
	v_cvt_pk_bf16_f32 v3, v4, v5
	v_lshlrev_b64 v[4:5], 12, v[10:11]
	v_lshl_add_u64 v[4:5], s[4:5], 0, v[4:5]
	v_lshl_add_u64 v[4:5], v[4:5], 0, s[26:27]
	v_lshl_add_u64 v[4:5], v[4:5], 0, v[170:171]
	flat_store_dwordx4 v[4:5], v[0:3] offset:2048
	s_branch .LBB0_1290
